# v58
# baseline (speedup 1.0000x reference)
.LBB0_73:
	s_cmp_eq_u32 s15, 0x30400
	s_mov_b32 s2, 0x10000
	s_and_b32 s2, s13, 0x10000
	s_xor_b32 s10, s2, 0x10000
	s_add_i32 s16, s21, s10
	s_add_i32 s17, s15, 0xfffd0000
	s_add_i32 s30, s16, 0x8000
	s_mov_b32 s10, s66
	s_mov_b32 s11, s67
	s_waitcnt lgkmcnt(0)
	v_add_u32_e32 v228, s2, v138
	v_add_u32_e32 v229, s2, v136
	ds_read_b128 v[132:135], v229 offset:0
	ds_read_b128 v[140:143], v229 offset:0x800
	ds_read_b128 v[144:147], v229 offset:0x1000
	ds_read_b128 v[148:151], v229 offset:0x1800
	ds_read_b128 v[152:155], v228 offset:0
	ds_read_b128 v[156:159], v228 offset:0x800
	s_mov_b32 m0, s16
	s_nop 0
	buffer_load_dwordx4 v131, s[64:67], s17 offen lds
	s_mov_b32 m0, s30
	s_nop 0
	buffer_load_dwordx4 v131, s[8:11], s17 offen lds
	s_add_i32 m0, s16, 0x2000
	s_add_i32 s17, s15, 0xfffe0000
	buffer_load_dwordx4 v131, s[64:67], s17 offen lds
	s_add_i32 m0, s16, 0xa000
	s_nop 0
	buffer_load_dwordx4 v131, s[8:11], s17 offen lds
	s_add_i32 m0, s16, 0x4000
	s_add_i32 s17, s15, 0xffff0000
	buffer_load_dwordx4 v131, s[64:67], s17 offen lds
	ds_read_b128 v[160:163], v228 offset:0x1000
	v_xor_b32_e32 v176, 64, v228
	s_waitcnt lgkmcnt(2)
	v_mfma_f32_16x16x32_bf16 v[126:129], v[152:155], v[132:135], 0
	v_mfma_f32_16x16x32_bf16 v[122:125], v[152:155], v[140:143], 0
	v_mfma_f32_16x16x32_bf16 v[118:121], v[152:155], v[144:147], 0
	v_mfma_f32_16x16x32_bf16 v[114:117], v[152:155], v[148:151], 0
	s_add_i32 m0, s16, 0xc000
	s_nop 0
	buffer_load_dwordx4 v131, s[8:11], s17 offen lds
	ds_read_b128 v[152:155], v228 offset:0x1800
	s_waitcnt lgkmcnt(2)
	v_mfma_f32_16x16x32_bf16 v[110:113], v[156:159], v[132:135], 0
	v_mfma_f32_16x16x32_bf16 v[106:109], v[156:159], v[140:143], 0
	v_mfma_f32_16x16x32_bf16 v[102:105], v[156:159], v[144:147], 0
	v_mfma_f32_16x16x32_bf16 v[98:101], v[156:159], v[148:151], 0
	s_add_i32 m0, s16, 0x6000
	s_nop 0
	buffer_load_dwordx4 v131, s[64:67], s15 offen lds
	ds_read_b128 v[156:159], v228 offset:0x2000
	s_waitcnt lgkmcnt(2)
	v_mfma_f32_16x16x32_bf16 v[94:97], v[160:163], v[132:135], 0
	v_mfma_f32_16x16x32_bf16 v[90:93], v[160:163], v[140:143], 0
	v_mfma_f32_16x16x32_bf16 v[86:89], v[160:163], v[144:147], 0
	v_mfma_f32_16x16x32_bf16 v[82:85], v[160:163], v[148:151], 0
	s_add_i32 m0, s16, 0xe000
	s_nop 0
	buffer_load_dwordx4 v131, s[8:11], s15 offen lds
	ds_read_b128 v[160:163], v228 offset:0x2800
	s_waitcnt lgkmcnt(2)
	v_mfma_f32_16x16x32_bf16 v[78:81], v[152:155], v[132:135], 0
	v_mfma_f32_16x16x32_bf16 v[74:77], v[152:155], v[140:143], 0
	v_mfma_f32_16x16x32_bf16 v[70:73], v[152:155], v[144:147], 0
	v_mfma_f32_16x16x32_bf16 v[66:69], v[152:155], v[148:151], 0
	ds_read_b128 v[152:155], v228 offset:0x3000
	s_waitcnt lgkmcnt(2)
	v_mfma_f32_16x16x32_bf16 v[62:65], v[156:159], v[132:135], 0
	v_mfma_f32_16x16x32_bf16 v[58:61], v[156:159], v[140:143], 0
	v_mfma_f32_16x16x32_bf16 v[54:57], v[156:159], v[144:147], 0
	v_mfma_f32_16x16x32_bf16 v[50:53], v[156:159], v[148:151], 0
	ds_read_b128 v[156:159], v228 offset:0x3800
	s_waitcnt lgkmcnt(2)
	v_xor_b32_e32 v0, 64, v229
	v_mfma_f32_16x16x32_bf16 v[46:49], v[160:163], v[132:135], 0
	v_mfma_f32_16x16x32_bf16 v[42:45], v[160:163], v[140:143], 0
	v_mfma_f32_16x16x32_bf16 v[38:41], v[160:163], v[144:147], 0
	v_mfma_f32_16x16x32_bf16 v[34:37], v[160:163], v[148:151], 0
	ds_read_b128 v[160:163], v0 offset:0
	ds_read_b128 v[164:167], v0 offset:0x800
	ds_read_b128 v[168:171], v0 offset:0x1000
	s_waitcnt lgkmcnt(4)
	v_mfma_f32_16x16x32_bf16 v[30:33], v[152:155], v[132:135], 0
	v_mfma_f32_16x16x32_bf16 v[26:29], v[152:155], v[140:143], 0
	v_mfma_f32_16x16x32_bf16 v[22:25], v[152:155], v[144:147], 0
	v_mfma_f32_16x16x32_bf16 v[18:21], v[152:155], v[148:151], 0
	ds_read_b128 v[232:235], v0 offset:0x1800
	ds_read_b128 v[172:175], v176 offset:0
	ds_read_b128 v[202:205], v176 offset:0x800
	s_waitcnt lgkmcnt(6)
	v_mfma_f32_16x16x32_bf16 v[14:17], v[156:159], v[132:135], 0
	v_mfma_f32_16x16x32_bf16 v[10:13], v[156:159], v[140:143], 0
	v_mfma_f32_16x16x32_bf16 v[6:9], v[156:159], v[144:147], 0
	v_mfma_f32_16x16x32_bf16 v[2:5], v[156:159], v[148:151], 0
	ds_read_b128 v[132:135], v176 offset:0x1000
	ds_read_b128 v[236:239], v176 offset:0x2800
	s_waitcnt lgkmcnt(3)
	v_mfma_f32_16x16x32_bf16 v[126:129], v[172:175], v[160:163], v[126:129]
	v_mfma_f32_16x16x32_bf16 v[122:125], v[172:175], v[164:167], v[122:125]
	v_mfma_f32_16x16x32_bf16 v[118:121], v[172:175], v[168:171], v[118:121]
	v_mfma_f32_16x16x32_bf16 v[114:117], v[172:175], v[232:235], v[114:117]
	ds_read_b128 v[140:143], v176 offset:0x1800
	ds_read_b128 v[240:243], v176 offset:0x3000
	s_waitcnt lgkmcnt(4)
	v_mfma_f32_16x16x32_bf16 v[110:113], v[202:205], v[160:163], v[110:113]
	v_mfma_f32_16x16x32_bf16 v[106:109], v[202:205], v[164:167], v[106:109]
	v_mfma_f32_16x16x32_bf16 v[102:105], v[202:205], v[168:171], v[102:105]
	v_mfma_f32_16x16x32_bf16 v[98:101], v[202:205], v[232:235], v[98:101]
	ds_read_b128 v[144:147], v176 offset:0x2000
	ds_read_b128 v[244:247], v176 offset:0x3800
	s_waitcnt lgkmcnt(5)
	v_mfma_f32_16x16x32_bf16 v[94:97], v[132:135], v[160:163], v[94:97]
	v_mfma_f32_16x16x32_bf16 v[90:93], v[132:135], v[164:167], v[90:93]
	v_mfma_f32_16x16x32_bf16 v[86:89], v[132:135], v[168:171], v[86:89]
	v_mfma_f32_16x16x32_bf16 v[82:85], v[132:135], v[232:235], v[82:85]
	s_waitcnt lgkmcnt(3)
	v_mfma_f32_16x16x32_bf16 v[78:81], v[140:143], v[160:163], v[78:81]
	v_mfma_f32_16x16x32_bf16 v[74:77], v[140:143], v[164:167], v[74:77]
	v_mfma_f32_16x16x32_bf16 v[70:73], v[140:143], v[168:171], v[70:73]
	v_mfma_f32_16x16x32_bf16 v[66:69], v[140:143], v[232:235], v[66:69]
	s_waitcnt lgkmcnt(1)
	v_mfma_f32_16x16x32_bf16 v[62:65], v[144:147], v[160:163], v[62:65]
	v_mfma_f32_16x16x32_bf16 v[58:61], v[144:147], v[164:167], v[58:61]
	v_mfma_f32_16x16x32_bf16 v[54:57], v[144:147], v[168:171], v[54:57]
	v_mfma_f32_16x16x32_bf16 v[50:53], v[144:147], v[232:235], v[50:53]
	s_waitcnt lgkmcnt(0)
	s_waitcnt vmcnt(0)
	s_add_i32 s13, s13, 0x10000
	s_addk_i32 s15, 0x80
	s_cmp_eq_u32 s15, 0x30400
	s_mov_b32 s2, 0x10000
	s_barrier
	s_cbranch_scc0 .Lrot3_top_l
	s_branch .Lrot3_top_n
.Lrot3_top_l:
	s_and_b32 s2, s13, 0x10000
	s_xor_b32 s10, s2, 0x10000
	s_add_i32 s16, s21, s10
	s_add_i32 s17, s15, 0xfffd0000
	s_add_i32 s30, s16, 0x8000
	s_mov_b32 s10, s66
	s_mov_b32 s11, s67
	v_add_u32_e32 v228, s2, v138
	v_add_u32_e32 v229, s2, v136
	ds_read_b128 v[132:135], v229 offset:0
	ds_read_b128 v[140:143], v229 offset:0x800
	ds_read_b128 v[144:147], v229 offset:0x1000
	ds_read_b128 v[148:151], v229 offset:0x1800
	ds_read_b128 v[152:155], v228 offset:0
	ds_read_b128 v[156:159], v228 offset:0x800
	s_mov_b32 m0, s16
	s_nop 0
	buffer_load_dwordx4 v131, s[64:67], s17 offen lds
	s_mov_b32 m0, s30
	s_nop 0
	buffer_load_dwordx4 v131, s[8:11], s17 offen lds
	v_mfma_f32_16x16x32_bf16 v[46:49], v[236:239], v[160:163], v[46:49]
	v_mfma_f32_16x16x32_bf16 v[42:45], v[236:239], v[164:167], v[42:45]
	v_mfma_f32_16x16x32_bf16 v[38:41], v[236:239], v[168:171], v[38:41]
	v_mfma_f32_16x16x32_bf16 v[34:37], v[236:239], v[232:235], v[34:37]
	s_add_i32 m0, s16, 0x2000
	s_add_i32 s17, s15, 0xfffe0000
	buffer_load_dwordx4 v131, s[64:67], s17 offen lds
	v_mfma_f32_16x16x32_bf16 v[30:33], v[240:243], v[160:163], v[30:33]
	v_mfma_f32_16x16x32_bf16 v[26:29], v[240:243], v[164:167], v[26:29]
	v_mfma_f32_16x16x32_bf16 v[22:25], v[240:243], v[168:171], v[22:25]
	v_mfma_f32_16x16x32_bf16 v[18:21], v[240:243], v[232:235], v[18:21]
	s_add_i32 m0, s16, 0xa000
	s_nop 0
	buffer_load_dwordx4 v131, s[8:11], s17 offen lds
	v_mfma_f32_16x16x32_bf16 v[14:17], v[244:247], v[160:163], v[14:17]
	v_mfma_f32_16x16x32_bf16 v[10:13], v[244:247], v[164:167], v[10:13]
	v_mfma_f32_16x16x32_bf16 v[6:9], v[244:247], v[168:171], v[6:9]
	v_mfma_f32_16x16x32_bf16 v[2:5], v[244:247], v[232:235], v[2:5]
	s_add_i32 m0, s16, 0x4000
	s_add_i32 s17, s15, 0xffff0000
	buffer_load_dwordx4 v131, s[64:67], s17 offen lds
	ds_read_b128 v[160:163], v228 offset:0x1000
	v_xor_b32_e32 v176, 64, v228
.Lrot3_mid_l:
	s_waitcnt lgkmcnt(2)
	v_mfma_f32_16x16x32_bf16 v[126:129], v[152:155], v[132:135], v[126:129]
	v_mfma_f32_16x16x32_bf16 v[122:125], v[152:155], v[140:143], v[122:125]
	v_mfma_f32_16x16x32_bf16 v[118:121], v[152:155], v[144:147], v[118:121]
	v_mfma_f32_16x16x32_bf16 v[114:117], v[152:155], v[148:151], v[114:117]
	s_add_i32 m0, s16, 0xc000
	s_nop 0
	buffer_load_dwordx4 v131, s[8:11], s17 offen lds
	ds_read_b128 v[152:155], v228 offset:0x1800
	s_waitcnt lgkmcnt(2)
	v_mfma_f32_16x16x32_bf16 v[110:113], v[156:159], v[132:135], v[110:113]
	v_mfma_f32_16x16x32_bf16 v[106:109], v[156:159], v[140:143], v[106:109]
	v_mfma_f32_16x16x32_bf16 v[102:105], v[156:159], v[144:147], v[102:105]
	v_mfma_f32_16x16x32_bf16 v[98:101], v[156:159], v[148:151], v[98:101]
	s_add_i32 m0, s16, 0x6000
	s_nop 0
	buffer_load_dwordx4 v131, s[64:67], s15 offen lds
	ds_read_b128 v[156:159], v228 offset:0x2000
	s_waitcnt lgkmcnt(2)
	v_mfma_f32_16x16x32_bf16 v[94:97], v[160:163], v[132:135], v[94:97]
	v_mfma_f32_16x16x32_bf16 v[90:93], v[160:163], v[140:143], v[90:93]
	v_mfma_f32_16x16x32_bf16 v[86:89], v[160:163], v[144:147], v[86:89]
	v_mfma_f32_16x16x32_bf16 v[82:85], v[160:163], v[148:151], v[82:85]
	s_add_i32 m0, s16, 0xe000
	s_nop 0
	buffer_load_dwordx4 v131, s[8:11], s15 offen lds
	ds_read_b128 v[160:163], v228 offset:0x2800
	s_waitcnt lgkmcnt(2)
	v_mfma_f32_16x16x32_bf16 v[78:81], v[152:155], v[132:135], v[78:81]
	v_mfma_f32_16x16x32_bf16 v[74:77], v[152:155], v[140:143], v[74:77]
	v_mfma_f32_16x16x32_bf16 v[70:73], v[152:155], v[144:147], v[70:73]
	v_mfma_f32_16x16x32_bf16 v[66:69], v[152:155], v[148:151], v[66:69]
	ds_read_b128 v[152:155], v228 offset:0x3000
	s_waitcnt lgkmcnt(2)
	v_mfma_f32_16x16x32_bf16 v[62:65], v[156:159], v[132:135], v[62:65]
	v_mfma_f32_16x16x32_bf16 v[58:61], v[156:159], v[140:143], v[58:61]
	v_mfma_f32_16x16x32_bf16 v[54:57], v[156:159], v[144:147], v[54:57]
	v_mfma_f32_16x16x32_bf16 v[50:53], v[156:159], v[148:151], v[50:53]
	ds_read_b128 v[156:159], v228 offset:0x3800
	s_waitcnt lgkmcnt(2)
	v_xor_b32_e32 v0, 64, v229
	v_mfma_f32_16x16x32_bf16 v[46:49], v[160:163], v[132:135], v[46:49]
	v_mfma_f32_16x16x32_bf16 v[42:45], v[160:163], v[140:143], v[42:45]
	v_mfma_f32_16x16x32_bf16 v[38:41], v[160:163], v[144:147], v[38:41]
	v_mfma_f32_16x16x32_bf16 v[34:37], v[160:163], v[148:151], v[34:37]
	ds_read_b128 v[160:163], v0 offset:0
	ds_read_b128 v[164:167], v0 offset:0x800
	ds_read_b128 v[168:171], v0 offset:0x1000
	s_waitcnt lgkmcnt(4)
	v_mfma_f32_16x16x32_bf16 v[30:33], v[152:155], v[132:135], v[30:33]
	v_mfma_f32_16x16x32_bf16 v[26:29], v[152:155], v[140:143], v[26:29]
	v_mfma_f32_16x16x32_bf16 v[22:25], v[152:155], v[144:147], v[22:25]
	v_mfma_f32_16x16x32_bf16 v[18:21], v[152:155], v[148:151], v[18:21]
	ds_read_b128 v[232:235], v0 offset:0x1800
	ds_read_b128 v[172:175], v176 offset:0
	ds_read_b128 v[202:205], v176 offset:0x800
	s_waitcnt lgkmcnt(6)
	v_mfma_f32_16x16x32_bf16 v[14:17], v[156:159], v[132:135], v[14:17]
	v_mfma_f32_16x16x32_bf16 v[10:13], v[156:159], v[140:143], v[10:13]
	v_mfma_f32_16x16x32_bf16 v[6:9], v[156:159], v[144:147], v[6:9]
	v_mfma_f32_16x16x32_bf16 v[2:5], v[156:159], v[148:151], v[2:5]
	ds_read_b128 v[132:135], v176 offset:0x1000
	ds_read_b128 v[236:239], v176 offset:0x2800
	s_waitcnt lgkmcnt(3)
	v_mfma_f32_16x16x32_bf16 v[126:129], v[172:175], v[160:163], v[126:129]
	v_mfma_f32_16x16x32_bf16 v[122:125], v[172:175], v[164:167], v[122:125]
	v_mfma_f32_16x16x32_bf16 v[118:121], v[172:175], v[168:171], v[118:121]
	v_mfma_f32_16x16x32_bf16 v[114:117], v[172:175], v[232:235], v[114:117]
	ds_read_b128 v[140:143], v176 offset:0x1800
	ds_read_b128 v[240:243], v176 offset:0x3000
	s_waitcnt lgkmcnt(4)
	v_mfma_f32_16x16x32_bf16 v[110:113], v[202:205], v[160:163], v[110:113]
	v_mfma_f32_16x16x32_bf16 v[106:109], v[202:205], v[164:167], v[106:109]
	v_mfma_f32_16x16x32_bf16 v[102:105], v[202:205], v[168:171], v[102:105]
	v_mfma_f32_16x16x32_bf16 v[98:101], v[202:205], v[232:235], v[98:101]
	ds_read_b128 v[144:147], v176 offset:0x2000
	ds_read_b128 v[244:247], v176 offset:0x3800
	s_waitcnt lgkmcnt(5)
	v_mfma_f32_16x16x32_bf16 v[94:97], v[132:135], v[160:163], v[94:97]
	v_mfma_f32_16x16x32_bf16 v[90:93], v[132:135], v[164:167], v[90:93]
	v_mfma_f32_16x16x32_bf16 v[86:89], v[132:135], v[168:171], v[86:89]
	v_mfma_f32_16x16x32_bf16 v[82:85], v[132:135], v[232:235], v[82:85]
	s_waitcnt lgkmcnt(3)
	v_mfma_f32_16x16x32_bf16 v[78:81], v[140:143], v[160:163], v[78:81]
	v_mfma_f32_16x16x32_bf16 v[74:77], v[140:143], v[164:167], v[74:77]
	v_mfma_f32_16x16x32_bf16 v[70:73], v[140:143], v[168:171], v[70:73]
	v_mfma_f32_16x16x32_bf16 v[66:69], v[140:143], v[232:235], v[66:69]
	s_waitcnt lgkmcnt(1)
	v_mfma_f32_16x16x32_bf16 v[62:65], v[144:147], v[160:163], v[62:65]
	v_mfma_f32_16x16x32_bf16 v[58:61], v[144:147], v[164:167], v[58:61]
	v_mfma_f32_16x16x32_bf16 v[54:57], v[144:147], v[168:171], v[54:57]
	v_mfma_f32_16x16x32_bf16 v[50:53], v[144:147], v[232:235], v[50:53]
	s_waitcnt lgkmcnt(0)
	s_waitcnt vmcnt(0)
	s_add_i32 s13, s13, 0x10000
	s_addk_i32 s15, 0x80
	s_cmp_eq_u32 s15, 0x30400
	s_mov_b32 s2, 0x10000
	s_barrier
	s_cbranch_scc0 .Lrot3_top_l
.Lrot3_top_n:
	v_add_u32_e32 v228, s2, v138
	v_add_u32_e32 v229, s2, v136
	ds_read_b128 v[132:135], v229 offset:0
	ds_read_b128 v[140:143], v229 offset:0x800
	ds_read_b128 v[144:147], v229 offset:0x1000
	ds_read_b128 v[148:151], v229 offset:0x1800
	ds_read_b128 v[152:155], v228 offset:0
	ds_read_b128 v[156:159], v228 offset:0x800
	v_mfma_f32_16x16x32_bf16 v[46:49], v[236:239], v[160:163], v[46:49]
	v_mfma_f32_16x16x32_bf16 v[42:45], v[236:239], v[164:167], v[42:45]
	v_mfma_f32_16x16x32_bf16 v[38:41], v[236:239], v[168:171], v[38:41]
	v_mfma_f32_16x16x32_bf16 v[34:37], v[236:239], v[232:235], v[34:37]
	v_mfma_f32_16x16x32_bf16 v[30:33], v[240:243], v[160:163], v[30:33]
	v_mfma_f32_16x16x32_bf16 v[26:29], v[240:243], v[164:167], v[26:29]
	v_mfma_f32_16x16x32_bf16 v[22:25], v[240:243], v[168:171], v[22:25]
	v_mfma_f32_16x16x32_bf16 v[18:21], v[240:243], v[232:235], v[18:21]
	v_mfma_f32_16x16x32_bf16 v[14:17], v[244:247], v[160:163], v[14:17]
	v_mfma_f32_16x16x32_bf16 v[10:13], v[244:247], v[164:167], v[10:13]
	v_mfma_f32_16x16x32_bf16 v[6:9], v[244:247], v[168:171], v[6:9]
	v_mfma_f32_16x16x32_bf16 v[2:5], v[244:247], v[232:235], v[2:5]
	ds_read_b128 v[160:163], v228 offset:0x1000
	v_xor_b32_e32 v176, 64, v228
	s_waitcnt lgkmcnt(2)
	v_mfma_f32_16x16x32_bf16 v[126:129], v[152:155], v[132:135], v[126:129]
	v_mfma_f32_16x16x32_bf16 v[122:125], v[152:155], v[140:143], v[122:125]
	v_mfma_f32_16x16x32_bf16 v[118:121], v[152:155], v[144:147], v[118:121]
	v_mfma_f32_16x16x32_bf16 v[114:117], v[152:155], v[148:151], v[114:117]
	ds_read_b128 v[152:155], v228 offset:0x1800
	s_waitcnt lgkmcnt(2)
	v_mfma_f32_16x16x32_bf16 v[110:113], v[156:159], v[132:135], v[110:113]
	v_mfma_f32_16x16x32_bf16 v[106:109], v[156:159], v[140:143], v[106:109]
	v_mfma_f32_16x16x32_bf16 v[102:105], v[156:159], v[144:147], v[102:105]
	v_mfma_f32_16x16x32_bf16 v[98:101], v[156:159], v[148:151], v[98:101]
	ds_read_b128 v[156:159], v228 offset:0x2000
	s_waitcnt lgkmcnt(2)
	v_mfma_f32_16x16x32_bf16 v[94:97], v[160:163], v[132:135], v[94:97]
	v_mfma_f32_16x16x32_bf16 v[90:93], v[160:163], v[140:143], v[90:93]
	v_mfma_f32_16x16x32_bf16 v[86:89], v[160:163], v[144:147], v[86:89]
	v_mfma_f32_16x16x32_bf16 v[82:85], v[160:163], v[148:151], v[82:85]
	ds_read_b128 v[160:163], v228 offset:0x2800
	s_waitcnt lgkmcnt(2)
	v_mfma_f32_16x16x32_bf16 v[78:81], v[152:155], v[132:135], v[78:81]
	v_mfma_f32_16x16x32_bf16 v[74:77], v[152:155], v[140:143], v[74:77]
	v_mfma_f32_16x16x32_bf16 v[70:73], v[152:155], v[144:147], v[70:73]
	v_mfma_f32_16x16x32_bf16 v[66:69], v[152:155], v[148:151], v[66:69]
	ds_read_b128 v[152:155], v228 offset:0x3000
	s_waitcnt lgkmcnt(2)
	v_mfma_f32_16x16x32_bf16 v[62:65], v[156:159], v[132:135], v[62:65]
	v_mfma_f32_16x16x32_bf16 v[58:61], v[156:159], v[140:143], v[58:61]
	v_mfma_f32_16x16x32_bf16 v[54:57], v[156:159], v[144:147], v[54:57]
	v_mfma_f32_16x16x32_bf16 v[50:53], v[156:159], v[148:151], v[50:53]
	ds_read_b128 v[156:159], v228 offset:0x3800
	s_waitcnt lgkmcnt(2)
	v_xor_b32_e32 v0, 64, v229
	v_mfma_f32_16x16x32_bf16 v[46:49], v[160:163], v[132:135], v[46:49]
	v_mfma_f32_16x16x32_bf16 v[42:45], v[160:163], v[140:143], v[42:45]
	v_mfma_f32_16x16x32_bf16 v[38:41], v[160:163], v[144:147], v[38:41]
	v_mfma_f32_16x16x32_bf16 v[34:37], v[160:163], v[148:151], v[34:37]
	ds_read_b128 v[160:163], v0 offset:0
	ds_read_b128 v[164:167], v0 offset:0x800
	ds_read_b128 v[168:171], v0 offset:0x1000
	s_waitcnt lgkmcnt(4)
	v_mfma_f32_16x16x32_bf16 v[30:33], v[152:155], v[132:135], v[30:33]
	v_mfma_f32_16x16x32_bf16 v[26:29], v[152:155], v[140:143], v[26:29]
	v_mfma_f32_16x16x32_bf16 v[22:25], v[152:155], v[144:147], v[22:25]
	v_mfma_f32_16x16x32_bf16 v[18:21], v[152:155], v[148:151], v[18:21]
	ds_read_b128 v[232:235], v0 offset:0x1800
	ds_read_b128 v[172:175], v176 offset:0
	ds_read_b128 v[202:205], v176 offset:0x800
	s_waitcnt lgkmcnt(6)
	v_mfma_f32_16x16x32_bf16 v[14:17], v[156:159], v[132:135], v[14:17]
	v_mfma_f32_16x16x32_bf16 v[10:13], v[156:159], v[140:143], v[10:13]
	v_mfma_f32_16x16x32_bf16 v[6:9], v[156:159], v[144:147], v[6:9]
	v_mfma_f32_16x16x32_bf16 v[2:5], v[156:159], v[148:151], v[2:5]
	ds_read_b128 v[132:135], v176 offset:0x1000
	ds_read_b128 v[236:239], v176 offset:0x2800
	s_waitcnt lgkmcnt(3)
	v_mfma_f32_16x16x32_bf16 v[126:129], v[172:175], v[160:163], v[126:129]
	v_mfma_f32_16x16x32_bf16 v[122:125], v[172:175], v[164:167], v[122:125]
	v_mfma_f32_16x16x32_bf16 v[118:121], v[172:175], v[168:171], v[118:121]
	v_mfma_f32_16x16x32_bf16 v[114:117], v[172:175], v[232:235], v[114:117]
	ds_read_b128 v[140:143], v176 offset:0x1800
	ds_read_b128 v[240:243], v176 offset:0x3000
	s_waitcnt lgkmcnt(4)
	v_mfma_f32_16x16x32_bf16 v[110:113], v[202:205], v[160:163], v[110:113]
	v_mfma_f32_16x16x32_bf16 v[106:109], v[202:205], v[164:167], v[106:109]
	v_mfma_f32_16x16x32_bf16 v[102:105], v[202:205], v[168:171], v[102:105]
	v_mfma_f32_16x16x32_bf16 v[98:101], v[202:205], v[232:235], v[98:101]
	ds_read_b128 v[144:147], v176 offset:0x2000
	ds_read_b128 v[244:247], v176 offset:0x3800
	s_waitcnt lgkmcnt(5)
	v_mfma_f32_16x16x32_bf16 v[94:97], v[132:135], v[160:163], v[94:97]
	v_mfma_f32_16x16x32_bf16 v[90:93], v[132:135], v[164:167], v[90:93]
	v_mfma_f32_16x16x32_bf16 v[86:89], v[132:135], v[168:171], v[86:89]
	v_mfma_f32_16x16x32_bf16 v[82:85], v[132:135], v[232:235], v[82:85]
	s_waitcnt lgkmcnt(3)
	v_mfma_f32_16x16x32_bf16 v[78:81], v[140:143], v[160:163], v[78:81]
	v_mfma_f32_16x16x32_bf16 v[74:77], v[140:143], v[164:167], v[74:77]
	v_mfma_f32_16x16x32_bf16 v[70:73], v[140:143], v[168:171], v[70:73]
	v_mfma_f32_16x16x32_bf16 v[66:69], v[140:143], v[232:235], v[66:69]
	s_waitcnt lgkmcnt(1)
	v_mfma_f32_16x16x32_bf16 v[62:65], v[144:147], v[160:163], v[62:65]
	v_mfma_f32_16x16x32_bf16 v[58:61], v[144:147], v[164:167], v[58:61]
	v_mfma_f32_16x16x32_bf16 v[54:57], v[144:147], v[168:171], v[54:57]
	v_mfma_f32_16x16x32_bf16 v[50:53], v[144:147], v[232:235], v[50:53]
	s_waitcnt lgkmcnt(0)
	s_add_i32 s13, s13, 0x10000
	s_addk_i32 s15, 0x80
	s_barrier
	v_mfma_f32_16x16x32_bf16 v[46:49], v[236:239], v[160:163], v[46:49]
	v_mfma_f32_16x16x32_bf16 v[42:45], v[236:239], v[164:167], v[42:45]
	v_mfma_f32_16x16x32_bf16 v[38:41], v[236:239], v[168:171], v[38:41]
	v_mfma_f32_16x16x32_bf16 v[34:37], v[236:239], v[232:235], v[34:37]
	v_mfma_f32_16x16x32_bf16 v[30:33], v[240:243], v[160:163], v[30:33]
	v_mfma_f32_16x16x32_bf16 v[26:29], v[240:243], v[164:167], v[26:29]
	v_mfma_f32_16x16x32_bf16 v[22:25], v[240:243], v[168:171], v[22:25]
	v_mfma_f32_16x16x32_bf16 v[18:21], v[240:243], v[232:235], v[18:21]
	v_mfma_f32_16x16x32_bf16 v[14:17], v[244:247], v[160:163], v[14:17]
	v_mfma_f32_16x16x32_bf16 v[10:13], v[244:247], v[164:167], v[10:13]
	v_mfma_f32_16x16x32_bf16 v[6:9], v[244:247], v[168:171], v[6:9]
	v_mfma_f32_16x16x32_bf16 v[2:5], v[244:247], v[232:235], v[2:5]
	s_nop 7
	s_nop 7
	s_nop 3

.LBB0_271:
	s_cmp_eq_u32 s21, 0x60800
	s_mov_b32 s2, 0x10000
	s_and_b32 s2, s19, 0x10000
	s_xor_b32 s10, s2, 0x10000
	s_add_i32 s51, s29, s10
	s_add_i32 s52, s21, 0xfffa0000
	s_add_i32 s53, s51, 0x8000
	s_mov_b32 s10, s66
	s_mov_b32 s11, s67
	s_waitcnt lgkmcnt(0)
	v_add_u32_e32 v228, s2, v205
	v_add_u32_e32 v229, s2, v202
	ds_read_b128 v[130:133], v229 offset:0
	ds_read_b128 v[134:137], v229 offset:0x800
	ds_read_b128 v[138:141], v229 offset:0x1000
	ds_read_b128 v[142:145], v229 offset:0x1800
	ds_read_b128 v[146:149], v228 offset:0
	ds_read_b128 v[150:153], v228 offset:0x800
	s_mov_b32 m0, s51
	s_nop 0
	buffer_load_dwordx4 v173, s[64:67], s52 offen lds
	s_mov_b32 m0, s53
	s_nop 0
	buffer_load_dwordx4 v248, s[8:11], s52 offen lds
	s_add_i32 m0, s51, 0x2000
	s_add_i32 s52, s21, 0xfffc0000
	buffer_load_dwordx4 v173, s[64:67], s52 offen lds
	s_add_i32 m0, s51, 0xa000
	s_nop 0
	buffer_load_dwordx4 v248, s[8:11], s52 offen lds
	s_add_i32 m0, s51, 0x4000
	s_add_i32 s52, s21, 0xfffe0000
	buffer_load_dwordx4 v173, s[64:67], s52 offen lds
	ds_read_b128 v[154:157], v228 offset:0x1000
	v_xor_b32_e32 v177, 64, v228
	s_waitcnt lgkmcnt(2)
	v_mfma_f32_16x16x32_bf16 v[122:125], v[146:149], v[130:133], 0
	v_mfma_f32_16x16x32_bf16 v[126:129], v[146:149], v[134:137], 0
	v_mfma_f32_16x16x32_bf16 v[118:121], v[146:149], v[138:141], 0
	v_mfma_f32_16x16x32_bf16 v[114:117], v[146:149], v[142:145], 0
	s_add_i32 m0, s51, 0xc000
	s_nop 0
	buffer_load_dwordx4 v248, s[8:11], s52 offen lds
	ds_read_b128 v[146:149], v228 offset:0x1800
	s_waitcnt lgkmcnt(2)
	v_mfma_f32_16x16x32_bf16 v[110:113], v[150:153], v[130:133], 0
	v_mfma_f32_16x16x32_bf16 v[106:109], v[150:153], v[134:137], 0
	v_mfma_f32_16x16x32_bf16 v[102:105], v[150:153], v[138:141], 0
	v_mfma_f32_16x16x32_bf16 v[98:101], v[150:153], v[142:145], 0
	s_add_i32 m0, s51, 0x6000
	s_nop 0
	buffer_load_dwordx4 v173, s[64:67], s21 offen lds
	ds_read_b128 v[150:153], v228 offset:0x2000
	s_waitcnt lgkmcnt(2)
	v_mfma_f32_16x16x32_bf16 v[94:97], v[154:157], v[130:133], 0
	v_mfma_f32_16x16x32_bf16 v[90:93], v[154:157], v[134:137], 0
	v_mfma_f32_16x16x32_bf16 v[86:89], v[154:157], v[138:141], 0
	v_mfma_f32_16x16x32_bf16 v[82:85], v[154:157], v[142:145], 0
	s_add_i32 m0, s51, 0xe000
	s_nop 0
	buffer_load_dwordx4 v248, s[8:11], s21 offen lds
	ds_read_b128 v[154:157], v228 offset:0x2800
	s_waitcnt lgkmcnt(2)
	v_mfma_f32_16x16x32_bf16 v[78:81], v[146:149], v[130:133], 0
	v_mfma_f32_16x16x32_bf16 v[74:77], v[146:149], v[134:137], 0
	v_mfma_f32_16x16x32_bf16 v[70:73], v[146:149], v[138:141], 0
	v_mfma_f32_16x16x32_bf16 v[66:69], v[146:149], v[142:145], 0
	ds_read_b128 v[146:149], v228 offset:0x3000
	s_waitcnt lgkmcnt(2)
	v_mfma_f32_16x16x32_bf16 v[62:65], v[150:153], v[130:133], 0
	v_mfma_f32_16x16x32_bf16 v[58:61], v[150:153], v[134:137], 0
	v_mfma_f32_16x16x32_bf16 v[54:57], v[150:153], v[138:141], 0
	v_mfma_f32_16x16x32_bf16 v[50:53], v[150:153], v[142:145], 0
	ds_read_b128 v[150:153], v228 offset:0x3800
	s_waitcnt lgkmcnt(2)
	v_xor_b32_e32 v0, 64, v229
	v_mfma_f32_16x16x32_bf16 v[46:49], v[154:157], v[130:133], 0
	v_mfma_f32_16x16x32_bf16 v[42:45], v[154:157], v[134:137], 0
	v_mfma_f32_16x16x32_bf16 v[38:41], v[154:157], v[138:141], 0
	v_mfma_f32_16x16x32_bf16 v[34:37], v[154:157], v[142:145], 0
	ds_read_b128 v[154:157], v0 offset:0
	ds_read_b128 v[158:161], v0 offset:0x800
	ds_read_b128 v[162:165], v0 offset:0x1000
	s_waitcnt lgkmcnt(4)
	v_mfma_f32_16x16x32_bf16 v[30:33], v[146:149], v[130:133], 0
	v_mfma_f32_16x16x32_bf16 v[26:29], v[146:149], v[134:137], 0
	v_mfma_f32_16x16x32_bf16 v[22:25], v[146:149], v[138:141], 0
	v_mfma_f32_16x16x32_bf16 v[18:21], v[146:149], v[142:145], 0
	ds_read_b128 v[232:235], v0 offset:0x1800
	ds_read_b128 v[166:169], v177 offset:0
	ds_read_b128 v[206:209], v177 offset:0x800
	s_waitcnt lgkmcnt(6)
	v_mfma_f32_16x16x32_bf16 v[14:17], v[150:153], v[130:133], 0
	v_mfma_f32_16x16x32_bf16 v[10:13], v[150:153], v[134:137], 0
	v_mfma_f32_16x16x32_bf16 v[6:9], v[150:153], v[138:141], 0
	v_mfma_f32_16x16x32_bf16 v[2:5], v[150:153], v[142:145], 0
	ds_read_b128 v[130:133], v177 offset:0x1000
	ds_read_b128 v[236:239], v177 offset:0x2800
	s_waitcnt lgkmcnt(3)
	v_mfma_f32_16x16x32_bf16 v[122:125], v[166:169], v[154:157], v[122:125]
	v_mfma_f32_16x16x32_bf16 v[126:129], v[166:169], v[158:161], v[126:129]
	v_mfma_f32_16x16x32_bf16 v[118:121], v[166:169], v[162:165], v[118:121]
	v_mfma_f32_16x16x32_bf16 v[114:117], v[166:169], v[232:235], v[114:117]
	ds_read_b128 v[134:137], v177 offset:0x1800
	ds_read_b128 v[240:243], v177 offset:0x3000
	s_waitcnt lgkmcnt(4)
	v_mfma_f32_16x16x32_bf16 v[110:113], v[206:209], v[154:157], v[110:113]
	v_mfma_f32_16x16x32_bf16 v[106:109], v[206:209], v[158:161], v[106:109]
	v_mfma_f32_16x16x32_bf16 v[102:105], v[206:209], v[162:165], v[102:105]
	v_mfma_f32_16x16x32_bf16 v[98:101], v[206:209], v[232:235], v[98:101]
	ds_read_b128 v[138:141], v177 offset:0x2000
	ds_read_b128 v[244:247], v177 offset:0x3800
	s_waitcnt lgkmcnt(5)
	v_mfma_f32_16x16x32_bf16 v[94:97], v[130:133], v[154:157], v[94:97]
	v_mfma_f32_16x16x32_bf16 v[90:93], v[130:133], v[158:161], v[90:93]
	v_mfma_f32_16x16x32_bf16 v[86:89], v[130:133], v[162:165], v[86:89]
	v_mfma_f32_16x16x32_bf16 v[82:85], v[130:133], v[232:235], v[82:85]
	s_waitcnt lgkmcnt(3)
	v_mfma_f32_16x16x32_bf16 v[78:81], v[134:137], v[154:157], v[78:81]
	v_mfma_f32_16x16x32_bf16 v[74:77], v[134:137], v[158:161], v[74:77]
	v_mfma_f32_16x16x32_bf16 v[70:73], v[134:137], v[162:165], v[70:73]
	v_mfma_f32_16x16x32_bf16 v[66:69], v[134:137], v[232:235], v[66:69]
	s_waitcnt lgkmcnt(1)
	v_mfma_f32_16x16x32_bf16 v[62:65], v[138:141], v[154:157], v[62:65]
	v_mfma_f32_16x16x32_bf16 v[58:61], v[138:141], v[158:161], v[58:61]
	v_mfma_f32_16x16x32_bf16 v[54:57], v[138:141], v[162:165], v[54:57]
	v_mfma_f32_16x16x32_bf16 v[50:53], v[138:141], v[232:235], v[50:53]
	s_waitcnt lgkmcnt(0)
	s_waitcnt vmcnt(0)
	s_add_i32 s19, s19, 0x10000
	s_addk_i32 s21, 0x80
	s_cmp_eq_u32 s21, 0x60800
	s_mov_b32 s2, 0x10000
	s_barrier
	s_cbranch_scc0 .Lrot2_top_l
	s_branch .Lrot2_top_n
.Lrot2_top_l:
	s_and_b32 s2, s19, 0x10000
	s_xor_b32 s10, s2, 0x10000
	s_add_i32 s51, s29, s10
	s_add_i32 s52, s21, 0xfffa0000
	s_add_i32 s53, s51, 0x8000
	s_mov_b32 s10, s66
	s_mov_b32 s11, s67
	v_add_u32_e32 v228, s2, v205
	v_add_u32_e32 v229, s2, v202
	ds_read_b128 v[130:133], v229 offset:0
	ds_read_b128 v[134:137], v229 offset:0x800
	ds_read_b128 v[138:141], v229 offset:0x1000
	ds_read_b128 v[142:145], v229 offset:0x1800
	ds_read_b128 v[146:149], v228 offset:0
	ds_read_b128 v[150:153], v228 offset:0x800
	s_mov_b32 m0, s51
	s_nop 0
	buffer_load_dwordx4 v173, s[64:67], s52 offen lds
	s_mov_b32 m0, s53
	s_nop 0
	buffer_load_dwordx4 v248, s[8:11], s52 offen lds
	v_mfma_f32_16x16x32_bf16 v[46:49], v[236:239], v[154:157], v[46:49]
	v_mfma_f32_16x16x32_bf16 v[42:45], v[236:239], v[158:161], v[42:45]
	v_mfma_f32_16x16x32_bf16 v[38:41], v[236:239], v[162:165], v[38:41]
	v_mfma_f32_16x16x32_bf16 v[34:37], v[236:239], v[232:235], v[34:37]
	s_add_i32 m0, s51, 0x2000
	s_add_i32 s52, s21, 0xfffc0000
	buffer_load_dwordx4 v173, s[64:67], s52 offen lds
	v_mfma_f32_16x16x32_bf16 v[30:33], v[240:243], v[154:157], v[30:33]
	v_mfma_f32_16x16x32_bf16 v[26:29], v[240:243], v[158:161], v[26:29]
	v_mfma_f32_16x16x32_bf16 v[22:25], v[240:243], v[162:165], v[22:25]
	v_mfma_f32_16x16x32_bf16 v[18:21], v[240:243], v[232:235], v[18:21]
	s_add_i32 m0, s51, 0xa000
	s_nop 0
	buffer_load_dwordx4 v248, s[8:11], s52 offen lds
	v_mfma_f32_16x16x32_bf16 v[14:17], v[244:247], v[154:157], v[14:17]
	v_mfma_f32_16x16x32_bf16 v[10:13], v[244:247], v[158:161], v[10:13]
	v_mfma_f32_16x16x32_bf16 v[6:9], v[244:247], v[162:165], v[6:9]
	v_mfma_f32_16x16x32_bf16 v[2:5], v[244:247], v[232:235], v[2:5]
	s_add_i32 m0, s51, 0x4000
	s_add_i32 s52, s21, 0xfffe0000
	buffer_load_dwordx4 v173, s[64:67], s52 offen lds
	ds_read_b128 v[154:157], v228 offset:0x1000
	v_xor_b32_e32 v177, 64, v228
.Lrot2_mid_l:
	s_waitcnt lgkmcnt(2)
	v_mfma_f32_16x16x32_bf16 v[122:125], v[146:149], v[130:133], v[122:125]
	v_mfma_f32_16x16x32_bf16 v[126:129], v[146:149], v[134:137], v[126:129]
	v_mfma_f32_16x16x32_bf16 v[118:121], v[146:149], v[138:141], v[118:121]
	v_mfma_f32_16x16x32_bf16 v[114:117], v[146:149], v[142:145], v[114:117]
	s_add_i32 m0, s51, 0xc000
	s_nop 0
	buffer_load_dwordx4 v248, s[8:11], s52 offen lds
	ds_read_b128 v[146:149], v228 offset:0x1800
	s_waitcnt lgkmcnt(2)
	v_mfma_f32_16x16x32_bf16 v[110:113], v[150:153], v[130:133], v[110:113]
	v_mfma_f32_16x16x32_bf16 v[106:109], v[150:153], v[134:137], v[106:109]
	v_mfma_f32_16x16x32_bf16 v[102:105], v[150:153], v[138:141], v[102:105]
	v_mfma_f32_16x16x32_bf16 v[98:101], v[150:153], v[142:145], v[98:101]
	s_add_i32 m0, s51, 0x6000
	s_nop 0
	buffer_load_dwordx4 v173, s[64:67], s21 offen lds
	ds_read_b128 v[150:153], v228 offset:0x2000
	s_waitcnt lgkmcnt(2)
	v_mfma_f32_16x16x32_bf16 v[94:97], v[154:157], v[130:133], v[94:97]
	v_mfma_f32_16x16x32_bf16 v[90:93], v[154:157], v[134:137], v[90:93]
	v_mfma_f32_16x16x32_bf16 v[86:89], v[154:157], v[138:141], v[86:89]
	v_mfma_f32_16x16x32_bf16 v[82:85], v[154:157], v[142:145], v[82:85]
	s_add_i32 m0, s51, 0xe000
	s_nop 0
	buffer_load_dwordx4 v248, s[8:11], s21 offen lds
	ds_read_b128 v[154:157], v228 offset:0x2800
	s_waitcnt lgkmcnt(2)
	v_mfma_f32_16x16x32_bf16 v[78:81], v[146:149], v[130:133], v[78:81]
	v_mfma_f32_16x16x32_bf16 v[74:77], v[146:149], v[134:137], v[74:77]
	v_mfma_f32_16x16x32_bf16 v[70:73], v[146:149], v[138:141], v[70:73]
	v_mfma_f32_16x16x32_bf16 v[66:69], v[146:149], v[142:145], v[66:69]
	ds_read_b128 v[146:149], v228 offset:0x3000
	s_waitcnt lgkmcnt(2)
	v_mfma_f32_16x16x32_bf16 v[62:65], v[150:153], v[130:133], v[62:65]
	v_mfma_f32_16x16x32_bf16 v[58:61], v[150:153], v[134:137], v[58:61]
	v_mfma_f32_16x16x32_bf16 v[54:57], v[150:153], v[138:141], v[54:57]
	v_mfma_f32_16x16x32_bf16 v[50:53], v[150:153], v[142:145], v[50:53]
	ds_read_b128 v[150:153], v228 offset:0x3800
	s_waitcnt lgkmcnt(2)
	v_xor_b32_e32 v0, 64, v229
	v_mfma_f32_16x16x32_bf16 v[46:49], v[154:157], v[130:133], v[46:49]
	v_mfma_f32_16x16x32_bf16 v[42:45], v[154:157], v[134:137], v[42:45]
	v_mfma_f32_16x16x32_bf16 v[38:41], v[154:157], v[138:141], v[38:41]
	v_mfma_f32_16x16x32_bf16 v[34:37], v[154:157], v[142:145], v[34:37]
	ds_read_b128 v[154:157], v0 offset:0
	ds_read_b128 v[158:161], v0 offset:0x800
	ds_read_b128 v[162:165], v0 offset:0x1000
	s_waitcnt lgkmcnt(4)
	v_mfma_f32_16x16x32_bf16 v[30:33], v[146:149], v[130:133], v[30:33]
	v_mfma_f32_16x16x32_bf16 v[26:29], v[146:149], v[134:137], v[26:29]
	v_mfma_f32_16x16x32_bf16 v[22:25], v[146:149], v[138:141], v[22:25]
	v_mfma_f32_16x16x32_bf16 v[18:21], v[146:149], v[142:145], v[18:21]
	ds_read_b128 v[232:235], v0 offset:0x1800
	ds_read_b128 v[166:169], v177 offset:0
	ds_read_b128 v[206:209], v177 offset:0x800
	s_waitcnt lgkmcnt(6)
	v_mfma_f32_16x16x32_bf16 v[14:17], v[150:153], v[130:133], v[14:17]
	v_mfma_f32_16x16x32_bf16 v[10:13], v[150:153], v[134:137], v[10:13]
	v_mfma_f32_16x16x32_bf16 v[6:9], v[150:153], v[138:141], v[6:9]
	v_mfma_f32_16x16x32_bf16 v[2:5], v[150:153], v[142:145], v[2:5]
	ds_read_b128 v[130:133], v177 offset:0x1000
	ds_read_b128 v[236:239], v177 offset:0x2800
	s_waitcnt lgkmcnt(3)
	v_mfma_f32_16x16x32_bf16 v[122:125], v[166:169], v[154:157], v[122:125]
	v_mfma_f32_16x16x32_bf16 v[126:129], v[166:169], v[158:161], v[126:129]
	v_mfma_f32_16x16x32_bf16 v[118:121], v[166:169], v[162:165], v[118:121]
	v_mfma_f32_16x16x32_bf16 v[114:117], v[166:169], v[232:235], v[114:117]
	ds_read_b128 v[134:137], v177 offset:0x1800
	ds_read_b128 v[240:243], v177 offset:0x3000
	s_waitcnt lgkmcnt(4)
	v_mfma_f32_16x16x32_bf16 v[110:113], v[206:209], v[154:157], v[110:113]
	v_mfma_f32_16x16x32_bf16 v[106:109], v[206:209], v[158:161], v[106:109]
	v_mfma_f32_16x16x32_bf16 v[102:105], v[206:209], v[162:165], v[102:105]
	v_mfma_f32_16x16x32_bf16 v[98:101], v[206:209], v[232:235], v[98:101]
	ds_read_b128 v[138:141], v177 offset:0x2000
	ds_read_b128 v[244:247], v177 offset:0x3800
	s_waitcnt lgkmcnt(5)
	v_mfma_f32_16x16x32_bf16 v[94:97], v[130:133], v[154:157], v[94:97]
	v_mfma_f32_16x16x32_bf16 v[90:93], v[130:133], v[158:161], v[90:93]
	v_mfma_f32_16x16x32_bf16 v[86:89], v[130:133], v[162:165], v[86:89]
	v_mfma_f32_16x16x32_bf16 v[82:85], v[130:133], v[232:235], v[82:85]
	s_waitcnt lgkmcnt(3)
	v_mfma_f32_16x16x32_bf16 v[78:81], v[134:137], v[154:157], v[78:81]
	v_mfma_f32_16x16x32_bf16 v[74:77], v[134:137], v[158:161], v[74:77]
	v_mfma_f32_16x16x32_bf16 v[70:73], v[134:137], v[162:165], v[70:73]
	v_mfma_f32_16x16x32_bf16 v[66:69], v[134:137], v[232:235], v[66:69]
	s_waitcnt lgkmcnt(1)
	v_mfma_f32_16x16x32_bf16 v[62:65], v[138:141], v[154:157], v[62:65]
	v_mfma_f32_16x16x32_bf16 v[58:61], v[138:141], v[158:161], v[58:61]
	v_mfma_f32_16x16x32_bf16 v[54:57], v[138:141], v[162:165], v[54:57]
	v_mfma_f32_16x16x32_bf16 v[50:53], v[138:141], v[232:235], v[50:53]
	s_waitcnt lgkmcnt(0)
	s_waitcnt vmcnt(0)
	s_add_i32 s19, s19, 0x10000
	s_addk_i32 s21, 0x80
	s_cmp_eq_u32 s21, 0x60800
	s_mov_b32 s2, 0x10000
	s_barrier
	s_cbranch_scc0 .Lrot2_top_l
.Lrot2_top_n:
	v_add_u32_e32 v228, s2, v205
	v_add_u32_e32 v229, s2, v202
	ds_read_b128 v[130:133], v229 offset:0
	ds_read_b128 v[134:137], v229 offset:0x800
	ds_read_b128 v[138:141], v229 offset:0x1000
	ds_read_b128 v[142:145], v229 offset:0x1800
	ds_read_b128 v[146:149], v228 offset:0
	ds_read_b128 v[150:153], v228 offset:0x800
	v_mfma_f32_16x16x32_bf16 v[46:49], v[236:239], v[154:157], v[46:49]
	v_mfma_f32_16x16x32_bf16 v[42:45], v[236:239], v[158:161], v[42:45]
	v_mfma_f32_16x16x32_bf16 v[38:41], v[236:239], v[162:165], v[38:41]
	v_mfma_f32_16x16x32_bf16 v[34:37], v[236:239], v[232:235], v[34:37]
	v_mfma_f32_16x16x32_bf16 v[30:33], v[240:243], v[154:157], v[30:33]
	v_mfma_f32_16x16x32_bf16 v[26:29], v[240:243], v[158:161], v[26:29]
	v_mfma_f32_16x16x32_bf16 v[22:25], v[240:243], v[162:165], v[22:25]
	v_mfma_f32_16x16x32_bf16 v[18:21], v[240:243], v[232:235], v[18:21]
	v_mfma_f32_16x16x32_bf16 v[14:17], v[244:247], v[154:157], v[14:17]
	v_mfma_f32_16x16x32_bf16 v[10:13], v[244:247], v[158:161], v[10:13]
	v_mfma_f32_16x16x32_bf16 v[6:9], v[244:247], v[162:165], v[6:9]
	v_mfma_f32_16x16x32_bf16 v[2:5], v[244:247], v[232:235], v[2:5]
	ds_read_b128 v[154:157], v228 offset:0x1000
	v_xor_b32_e32 v177, 64, v228
	s_waitcnt lgkmcnt(2)
	v_mfma_f32_16x16x32_bf16 v[122:125], v[146:149], v[130:133], v[122:125]
	v_mfma_f32_16x16x32_bf16 v[126:129], v[146:149], v[134:137], v[126:129]
	v_mfma_f32_16x16x32_bf16 v[118:121], v[146:149], v[138:141], v[118:121]
	v_mfma_f32_16x16x32_bf16 v[114:117], v[146:149], v[142:145], v[114:117]
	ds_read_b128 v[146:149], v228 offset:0x1800
	s_waitcnt lgkmcnt(2)
	v_mfma_f32_16x16x32_bf16 v[110:113], v[150:153], v[130:133], v[110:113]
	v_mfma_f32_16x16x32_bf16 v[106:109], v[150:153], v[134:137], v[106:109]
	v_mfma_f32_16x16x32_bf16 v[102:105], v[150:153], v[138:141], v[102:105]
	v_mfma_f32_16x16x32_bf16 v[98:101], v[150:153], v[142:145], v[98:101]
	ds_read_b128 v[150:153], v228 offset:0x2000
	s_waitcnt lgkmcnt(2)
	v_mfma_f32_16x16x32_bf16 v[94:97], v[154:157], v[130:133], v[94:97]
	v_mfma_f32_16x16x32_bf16 v[90:93], v[154:157], v[134:137], v[90:93]
	v_mfma_f32_16x16x32_bf16 v[86:89], v[154:157], v[138:141], v[86:89]
	v_mfma_f32_16x16x32_bf16 v[82:85], v[154:157], v[142:145], v[82:85]
	ds_read_b128 v[154:157], v228 offset:0x2800
	s_waitcnt lgkmcnt(2)
	v_mfma_f32_16x16x32_bf16 v[78:81], v[146:149], v[130:133], v[78:81]
	v_mfma_f32_16x16x32_bf16 v[74:77], v[146:149], v[134:137], v[74:77]
	v_mfma_f32_16x16x32_bf16 v[70:73], v[146:149], v[138:141], v[70:73]
	v_mfma_f32_16x16x32_bf16 v[66:69], v[146:149], v[142:145], v[66:69]
	ds_read_b128 v[146:149], v228 offset:0x3000
	s_waitcnt lgkmcnt(2)
	v_mfma_f32_16x16x32_bf16 v[62:65], v[150:153], v[130:133], v[62:65]
	v_mfma_f32_16x16x32_bf16 v[58:61], v[150:153], v[134:137], v[58:61]
	v_mfma_f32_16x16x32_bf16 v[54:57], v[150:153], v[138:141], v[54:57]
	v_mfma_f32_16x16x32_bf16 v[50:53], v[150:153], v[142:145], v[50:53]
	ds_read_b128 v[150:153], v228 offset:0x3800
	s_waitcnt lgkmcnt(2)
	v_xor_b32_e32 v0, 64, v229
	v_mfma_f32_16x16x32_bf16 v[46:49], v[154:157], v[130:133], v[46:49]
	v_mfma_f32_16x16x32_bf16 v[42:45], v[154:157], v[134:137], v[42:45]
	v_mfma_f32_16x16x32_bf16 v[38:41], v[154:157], v[138:141], v[38:41]
	v_mfma_f32_16x16x32_bf16 v[34:37], v[154:157], v[142:145], v[34:37]
	ds_read_b128 v[154:157], v0 offset:0
	ds_read_b128 v[158:161], v0 offset:0x800
	ds_read_b128 v[162:165], v0 offset:0x1000
	s_waitcnt lgkmcnt(4)
	v_mfma_f32_16x16x32_bf16 v[30:33], v[146:149], v[130:133], v[30:33]
	v_mfma_f32_16x16x32_bf16 v[26:29], v[146:149], v[134:137], v[26:29]
	v_mfma_f32_16x16x32_bf16 v[22:25], v[146:149], v[138:141], v[22:25]
	v_mfma_f32_16x16x32_bf16 v[18:21], v[146:149], v[142:145], v[18:21]
	ds_read_b128 v[232:235], v0 offset:0x1800
	ds_read_b128 v[166:169], v177 offset:0
	ds_read_b128 v[206:209], v177 offset:0x800
	s_waitcnt lgkmcnt(6)
	v_mfma_f32_16x16x32_bf16 v[14:17], v[150:153], v[130:133], v[14:17]
	v_mfma_f32_16x16x32_bf16 v[10:13], v[150:153], v[134:137], v[10:13]
	v_mfma_f32_16x16x32_bf16 v[6:9], v[150:153], v[138:141], v[6:9]
	v_mfma_f32_16x16x32_bf16 v[2:5], v[150:153], v[142:145], v[2:5]
	ds_read_b128 v[130:133], v177 offset:0x1000
	ds_read_b128 v[236:239], v177 offset:0x2800
	s_waitcnt lgkmcnt(3)
	v_mfma_f32_16x16x32_bf16 v[122:125], v[166:169], v[154:157], v[122:125]
	v_mfma_f32_16x16x32_bf16 v[126:129], v[166:169], v[158:161], v[126:129]
	v_mfma_f32_16x16x32_bf16 v[118:121], v[166:169], v[162:165], v[118:121]
	v_mfma_f32_16x16x32_bf16 v[114:117], v[166:169], v[232:235], v[114:117]
	ds_read_b128 v[134:137], v177 offset:0x1800
	ds_read_b128 v[240:243], v177 offset:0x3000
	s_waitcnt lgkmcnt(4)
	v_mfma_f32_16x16x32_bf16 v[110:113], v[206:209], v[154:157], v[110:113]
	v_mfma_f32_16x16x32_bf16 v[106:109], v[206:209], v[158:161], v[106:109]
	v_mfma_f32_16x16x32_bf16 v[102:105], v[206:209], v[162:165], v[102:105]
	v_mfma_f32_16x16x32_bf16 v[98:101], v[206:209], v[232:235], v[98:101]
	ds_read_b128 v[138:141], v177 offset:0x2000
	ds_read_b128 v[244:247], v177 offset:0x3800
	s_waitcnt lgkmcnt(5)
	v_mfma_f32_16x16x32_bf16 v[94:97], v[130:133], v[154:157], v[94:97]
	v_mfma_f32_16x16x32_bf16 v[90:93], v[130:133], v[158:161], v[90:93]
	v_mfma_f32_16x16x32_bf16 v[86:89], v[130:133], v[162:165], v[86:89]
	v_mfma_f32_16x16x32_bf16 v[82:85], v[130:133], v[232:235], v[82:85]
	s_waitcnt lgkmcnt(3)
	v_mfma_f32_16x16x32_bf16 v[78:81], v[134:137], v[154:157], v[78:81]
	v_mfma_f32_16x16x32_bf16 v[74:77], v[134:137], v[158:161], v[74:77]
	v_mfma_f32_16x16x32_bf16 v[70:73], v[134:137], v[162:165], v[70:73]
	v_mfma_f32_16x16x32_bf16 v[66:69], v[134:137], v[232:235], v[66:69]
	s_waitcnt lgkmcnt(1)
	v_mfma_f32_16x16x32_bf16 v[62:65], v[138:141], v[154:157], v[62:65]
	v_mfma_f32_16x16x32_bf16 v[58:61], v[138:141], v[158:161], v[58:61]
	v_mfma_f32_16x16x32_bf16 v[54:57], v[138:141], v[162:165], v[54:57]
	v_mfma_f32_16x16x32_bf16 v[50:53], v[138:141], v[232:235], v[50:53]
	s_waitcnt lgkmcnt(0)
	s_add_i32 s19, s19, 0x10000
	s_addk_i32 s21, 0x80
	s_barrier
	v_mfma_f32_16x16x32_bf16 v[46:49], v[236:239], v[154:157], v[46:49]
	v_mfma_f32_16x16x32_bf16 v[42:45], v[236:239], v[158:161], v[42:45]
	v_mfma_f32_16x16x32_bf16 v[38:41], v[236:239], v[162:165], v[38:41]
	v_mfma_f32_16x16x32_bf16 v[34:37], v[236:239], v[232:235], v[34:37]
	v_mfma_f32_16x16x32_bf16 v[30:33], v[240:243], v[154:157], v[30:33]
	v_mfma_f32_16x16x32_bf16 v[26:29], v[240:243], v[158:161], v[26:29]
	v_mfma_f32_16x16x32_bf16 v[22:25], v[240:243], v[162:165], v[22:25]
	v_mfma_f32_16x16x32_bf16 v[18:21], v[240:243], v[232:235], v[18:21]
	v_mfma_f32_16x16x32_bf16 v[14:17], v[244:247], v[154:157], v[14:17]
	v_mfma_f32_16x16x32_bf16 v[10:13], v[244:247], v[158:161], v[10:13]
	v_mfma_f32_16x16x32_bf16 v[6:9], v[244:247], v[162:165], v[6:9]
	v_mfma_f32_16x16x32_bf16 v[2:5], v[244:247], v[232:235], v[2:5]
	s_nop 7
	s_nop 7
	s_nop 3

.LBB0_296:
	s_and_b32 s2, s44, 0x10000
	s_cmp_ge_u32 s41, s24
	s_xor_b32 s14, s2, 0x10000
	s_add_i32 s46, s26, s14
	s_add_i32 s47, s46, 0x8000
	s_mov_b32 s14, s66
	s_mov_b32 s15, s67
	s_waitcnt lgkmcnt(0)
	v_add_u32_e32 v228, s2, v143
	v_add_u32_e32 v229, s2, v133
	ds_read_b128 v[134:137], v229 offset:0
	ds_read_b128 v[138:141], v229 offset:0x800
	ds_read_b128 v[144:147], v229 offset:0x1000
	ds_read_b128 v[148:151], v229 offset:0x1800
	ds_read_b128 v[152:155], v228 offset:0
	ds_read_b128 v[156:159], v228 offset:0x800
	s_mov_b32 m0, s46
	s_nop 0
	buffer_load_dwordx4 v131, s[64:67], s45 offen lds
	s_mov_b32 m0, s47
	s_add_i32 s47, s27, s45
	buffer_load_dwordx4 v248, s[12:15], s45 offen lds
	s_add_i32 m0, s46, 0x2000
	s_nop 0
	buffer_load_dwordx4 v131, s[64:67], s47 offen lds
	s_add_i32 m0, s46, 0xa000
	s_nop 0
	buffer_load_dwordx4 v248, s[12:15], s47 offen lds
	s_add_i32 m0, s46, 0x4000
	s_add_i32 s47, s34, s45
	buffer_load_dwordx4 v131, s[64:67], s47 offen lds
	ds_read_b128 v[160:163], v228 offset:0x1000
	v_xor_b32_e32 v176, 64, v228
	s_waitcnt lgkmcnt(2)
	v_mfma_f32_16x16x32_bf16 v[126:129], v[152:155], v[134:137], 0
	v_mfma_f32_16x16x32_bf16 v[122:125], v[152:155], v[138:141], 0
	v_mfma_f32_16x16x32_bf16 v[118:121], v[152:155], v[144:147], 0
	v_mfma_f32_16x16x32_bf16 v[114:117], v[152:155], v[148:151], 0
	s_add_i32 m0, s46, 0xc000
	s_nop 0
	buffer_load_dwordx4 v248, s[12:15], s47 offen lds
	ds_read_b128 v[152:155], v228 offset:0x1800
	s_waitcnt lgkmcnt(2)
	v_mfma_f32_16x16x32_bf16 v[110:113], v[156:159], v[134:137], 0
	v_mfma_f32_16x16x32_bf16 v[106:109], v[156:159], v[138:141], 0
	v_mfma_f32_16x16x32_bf16 v[102:105], v[156:159], v[144:147], 0
	v_mfma_f32_16x16x32_bf16 v[98:101], v[156:159], v[148:151], 0
	s_add_i32 m0, s46, 0x6000
	s_add_i32 s47, s37, s45
	buffer_load_dwordx4 v131, s[64:67], s47 offen lds
	ds_read_b128 v[156:159], v228 offset:0x2000
	s_waitcnt lgkmcnt(2)
	v_mfma_f32_16x16x32_bf16 v[94:97], v[160:163], v[134:137], 0
	v_mfma_f32_16x16x32_bf16 v[90:93], v[160:163], v[138:141], 0
	v_mfma_f32_16x16x32_bf16 v[86:89], v[160:163], v[144:147], 0
	v_mfma_f32_16x16x32_bf16 v[82:85], v[160:163], v[148:151], 0
	s_add_i32 m0, s46, 0xe000
	s_nop 0
	buffer_load_dwordx4 v248, s[12:15], s47 offen lds
	ds_read_b128 v[160:163], v228 offset:0x2800
	s_waitcnt lgkmcnt(2)
	v_mfma_f32_16x16x32_bf16 v[78:81], v[152:155], v[134:137], 0
	v_mfma_f32_16x16x32_bf16 v[74:77], v[152:155], v[138:141], 0
	v_mfma_f32_16x16x32_bf16 v[70:73], v[152:155], v[144:147], 0
	v_mfma_f32_16x16x32_bf16 v[66:69], v[152:155], v[148:151], 0
	ds_read_b128 v[152:155], v228 offset:0x3000
	s_waitcnt lgkmcnt(2)
	v_mfma_f32_16x16x32_bf16 v[62:65], v[156:159], v[134:137], 0
	v_mfma_f32_16x16x32_bf16 v[58:61], v[156:159], v[138:141], 0
	v_mfma_f32_16x16x32_bf16 v[54:57], v[156:159], v[144:147], 0
	v_mfma_f32_16x16x32_bf16 v[50:53], v[156:159], v[148:151], 0
	ds_read_b128 v[156:159], v228 offset:0x3800
	s_waitcnt lgkmcnt(2)
	v_xor_b32_e32 v0, 64, v229
	v_mfma_f32_16x16x32_bf16 v[46:49], v[160:163], v[134:137], 0
	v_mfma_f32_16x16x32_bf16 v[42:45], v[160:163], v[138:141], 0
	v_mfma_f32_16x16x32_bf16 v[38:41], v[160:163], v[144:147], 0
	v_mfma_f32_16x16x32_bf16 v[34:37], v[160:163], v[148:151], 0
	ds_read_b128 v[160:163], v0 offset:0
	ds_read_b128 v[164:167], v0 offset:0x800
	ds_read_b128 v[168:171], v0 offset:0x1000
	s_waitcnt lgkmcnt(4)
	v_mfma_f32_16x16x32_bf16 v[30:33], v[152:155], v[134:137], 0
	v_mfma_f32_16x16x32_bf16 v[26:29], v[152:155], v[138:141], 0
	v_mfma_f32_16x16x32_bf16 v[22:25], v[152:155], v[144:147], 0
	v_mfma_f32_16x16x32_bf16 v[18:21], v[152:155], v[148:151], 0
	ds_read_b128 v[232:235], v0 offset:0x1800
	ds_read_b128 v[172:175], v176 offset:0
	ds_read_b128 v[202:205], v176 offset:0x800
	s_waitcnt lgkmcnt(6)
	v_mfma_f32_16x16x32_bf16 v[14:17], v[156:159], v[134:137], 0
	v_mfma_f32_16x16x32_bf16 v[10:13], v[156:159], v[138:141], 0
	v_mfma_f32_16x16x32_bf16 v[6:9], v[156:159], v[144:147], 0
	v_mfma_f32_16x16x32_bf16 v[2:5], v[156:159], v[148:151], 0
	ds_read_b128 v[134:137], v176 offset:0x1000
	ds_read_b128 v[236:239], v176 offset:0x2800
	s_waitcnt lgkmcnt(3)
	v_mfma_f32_16x16x32_bf16 v[126:129], v[172:175], v[160:163], v[126:129]
	v_mfma_f32_16x16x32_bf16 v[122:125], v[172:175], v[164:167], v[122:125]
	v_mfma_f32_16x16x32_bf16 v[118:121], v[172:175], v[168:171], v[118:121]
	v_mfma_f32_16x16x32_bf16 v[114:117], v[172:175], v[232:235], v[114:117]
	ds_read_b128 v[138:141], v176 offset:0x1800
	ds_read_b128 v[240:243], v176 offset:0x3000
	s_waitcnt lgkmcnt(4)
	v_mfma_f32_16x16x32_bf16 v[110:113], v[202:205], v[160:163], v[110:113]
	v_mfma_f32_16x16x32_bf16 v[106:109], v[202:205], v[164:167], v[106:109]
	v_mfma_f32_16x16x32_bf16 v[102:105], v[202:205], v[168:171], v[102:105]
	v_mfma_f32_16x16x32_bf16 v[98:101], v[202:205], v[232:235], v[98:101]
	ds_read_b128 v[144:147], v176 offset:0x2000
	ds_read_b128 v[244:247], v176 offset:0x3800
	s_waitcnt lgkmcnt(5)
	v_mfma_f32_16x16x32_bf16 v[94:97], v[134:137], v[160:163], v[94:97]
	v_mfma_f32_16x16x32_bf16 v[90:93], v[134:137], v[164:167], v[90:93]
	v_mfma_f32_16x16x32_bf16 v[86:89], v[134:137], v[168:171], v[86:89]
	v_mfma_f32_16x16x32_bf16 v[82:85], v[134:137], v[232:235], v[82:85]
	s_waitcnt lgkmcnt(3)
	v_mfma_f32_16x16x32_bf16 v[78:81], v[138:141], v[160:163], v[78:81]
	v_mfma_f32_16x16x32_bf16 v[74:77], v[138:141], v[164:167], v[74:77]
	v_mfma_f32_16x16x32_bf16 v[70:73], v[138:141], v[168:171], v[70:73]
	v_mfma_f32_16x16x32_bf16 v[66:69], v[138:141], v[232:235], v[66:69]
	s_waitcnt lgkmcnt(1)
	v_mfma_f32_16x16x32_bf16 v[62:65], v[144:147], v[160:163], v[62:65]
	v_mfma_f32_16x16x32_bf16 v[58:61], v[144:147], v[164:167], v[58:61]
	v_mfma_f32_16x16x32_bf16 v[54:57], v[144:147], v[168:171], v[54:57]
	v_mfma_f32_16x16x32_bf16 v[50:53], v[144:147], v[232:235], v[50:53]
	s_waitcnt lgkmcnt(0)
	s_waitcnt vmcnt(0)
	s_add_i32 s44, s44, 0x10000
	s_addk_i32 s45, 0x80
	s_add_i32 s41, s41, 1
	s_and_b32 s2, s44, 0x10000
	s_cmp_ge_u32 s41, s24
	s_barrier
	s_cbranch_scc0 .Lrot1_top_l
	s_branch .Lrot1_top_n
.Lrot1_top_l:
	s_xor_b32 s14, s2, 0x10000
	s_add_i32 s46, s26, s14
	s_add_i32 s47, s46, 0x8000
	s_mov_b32 s14, s66
	s_mov_b32 s15, s67
	v_add_u32_e32 v228, s2, v143
	v_add_u32_e32 v229, s2, v133
	ds_read_b128 v[134:137], v229 offset:0
	ds_read_b128 v[138:141], v229 offset:0x800
	ds_read_b128 v[144:147], v229 offset:0x1000
	ds_read_b128 v[148:151], v229 offset:0x1800
	ds_read_b128 v[152:155], v228 offset:0
	ds_read_b128 v[156:159], v228 offset:0x800
	s_mov_b32 m0, s46
	s_nop 0
	buffer_load_dwordx4 v131, s[64:67], s45 offen lds
	s_mov_b32 m0, s47
	s_add_i32 s47, s27, s45
	buffer_load_dwordx4 v248, s[12:15], s45 offen lds
	v_mfma_f32_16x16x32_bf16 v[46:49], v[236:239], v[160:163], v[46:49]
	v_mfma_f32_16x16x32_bf16 v[42:45], v[236:239], v[164:167], v[42:45]
	v_mfma_f32_16x16x32_bf16 v[38:41], v[236:239], v[168:171], v[38:41]
	v_mfma_f32_16x16x32_bf16 v[34:37], v[236:239], v[232:235], v[34:37]
	s_add_i32 m0, s46, 0x2000
	s_nop 0
	buffer_load_dwordx4 v131, s[64:67], s47 offen lds
	v_mfma_f32_16x16x32_bf16 v[30:33], v[240:243], v[160:163], v[30:33]
	v_mfma_f32_16x16x32_bf16 v[26:29], v[240:243], v[164:167], v[26:29]
	v_mfma_f32_16x16x32_bf16 v[22:25], v[240:243], v[168:171], v[22:25]
	v_mfma_f32_16x16x32_bf16 v[18:21], v[240:243], v[232:235], v[18:21]
	s_add_i32 m0, s46, 0xa000
	s_nop 0
	buffer_load_dwordx4 v248, s[12:15], s47 offen lds
	v_mfma_f32_16x16x32_bf16 v[14:17], v[244:247], v[160:163], v[14:17]
	v_mfma_f32_16x16x32_bf16 v[10:13], v[244:247], v[164:167], v[10:13]
	v_mfma_f32_16x16x32_bf16 v[6:9], v[244:247], v[168:171], v[6:9]
	v_mfma_f32_16x16x32_bf16 v[2:5], v[244:247], v[232:235], v[2:5]
	s_add_i32 m0, s46, 0x4000
	s_add_i32 s47, s34, s45
	buffer_load_dwordx4 v131, s[64:67], s47 offen lds
	ds_read_b128 v[160:163], v228 offset:0x1000
	v_xor_b32_e32 v176, 64, v228
.Lrot1_mid_l:
	s_waitcnt lgkmcnt(2)
	v_mfma_f32_16x16x32_bf16 v[126:129], v[152:155], v[134:137], v[126:129]
	v_mfma_f32_16x16x32_bf16 v[122:125], v[152:155], v[138:141], v[122:125]
	v_mfma_f32_16x16x32_bf16 v[118:121], v[152:155], v[144:147], v[118:121]
	v_mfma_f32_16x16x32_bf16 v[114:117], v[152:155], v[148:151], v[114:117]
	s_add_i32 m0, s46, 0xc000
	s_nop 0
	buffer_load_dwordx4 v248, s[12:15], s47 offen lds
	ds_read_b128 v[152:155], v228 offset:0x1800
	s_waitcnt lgkmcnt(2)
	v_mfma_f32_16x16x32_bf16 v[110:113], v[156:159], v[134:137], v[110:113]
	v_mfma_f32_16x16x32_bf16 v[106:109], v[156:159], v[138:141], v[106:109]
	v_mfma_f32_16x16x32_bf16 v[102:105], v[156:159], v[144:147], v[102:105]
	v_mfma_f32_16x16x32_bf16 v[98:101], v[156:159], v[148:151], v[98:101]
	s_add_i32 m0, s46, 0x6000
	s_add_i32 s47, s37, s45
	buffer_load_dwordx4 v131, s[64:67], s47 offen lds
	ds_read_b128 v[156:159], v228 offset:0x2000
	s_waitcnt lgkmcnt(2)
	v_mfma_f32_16x16x32_bf16 v[94:97], v[160:163], v[134:137], v[94:97]
	v_mfma_f32_16x16x32_bf16 v[90:93], v[160:163], v[138:141], v[90:93]
	v_mfma_f32_16x16x32_bf16 v[86:89], v[160:163], v[144:147], v[86:89]
	v_mfma_f32_16x16x32_bf16 v[82:85], v[160:163], v[148:151], v[82:85]
	s_add_i32 m0, s46, 0xe000
	s_nop 0
	buffer_load_dwordx4 v248, s[12:15], s47 offen lds
	ds_read_b128 v[160:163], v228 offset:0x2800
	s_waitcnt lgkmcnt(2)
	v_mfma_f32_16x16x32_bf16 v[78:81], v[152:155], v[134:137], v[78:81]
	v_mfma_f32_16x16x32_bf16 v[74:77], v[152:155], v[138:141], v[74:77]
	v_mfma_f32_16x16x32_bf16 v[70:73], v[152:155], v[144:147], v[70:73]
	v_mfma_f32_16x16x32_bf16 v[66:69], v[152:155], v[148:151], v[66:69]
	ds_read_b128 v[152:155], v228 offset:0x3000
	s_waitcnt lgkmcnt(2)
	v_mfma_f32_16x16x32_bf16 v[62:65], v[156:159], v[134:137], v[62:65]
	v_mfma_f32_16x16x32_bf16 v[58:61], v[156:159], v[138:141], v[58:61]
	v_mfma_f32_16x16x32_bf16 v[54:57], v[156:159], v[144:147], v[54:57]
	v_mfma_f32_16x16x32_bf16 v[50:53], v[156:159], v[148:151], v[50:53]
	ds_read_b128 v[156:159], v228 offset:0x3800
	s_waitcnt lgkmcnt(2)
	v_xor_b32_e32 v0, 64, v229
	v_mfma_f32_16x16x32_bf16 v[46:49], v[160:163], v[134:137], v[46:49]
	v_mfma_f32_16x16x32_bf16 v[42:45], v[160:163], v[138:141], v[42:45]
	v_mfma_f32_16x16x32_bf16 v[38:41], v[160:163], v[144:147], v[38:41]
	v_mfma_f32_16x16x32_bf16 v[34:37], v[160:163], v[148:151], v[34:37]
	ds_read_b128 v[160:163], v0 offset:0
	ds_read_b128 v[164:167], v0 offset:0x800
	ds_read_b128 v[168:171], v0 offset:0x1000
	s_waitcnt lgkmcnt(4)
	v_mfma_f32_16x16x32_bf16 v[30:33], v[152:155], v[134:137], v[30:33]
	v_mfma_f32_16x16x32_bf16 v[26:29], v[152:155], v[138:141], v[26:29]
	v_mfma_f32_16x16x32_bf16 v[22:25], v[152:155], v[144:147], v[22:25]
	v_mfma_f32_16x16x32_bf16 v[18:21], v[152:155], v[148:151], v[18:21]
	ds_read_b128 v[232:235], v0 offset:0x1800
	ds_read_b128 v[172:175], v176 offset:0
	ds_read_b128 v[202:205], v176 offset:0x800
	s_waitcnt lgkmcnt(6)
	v_mfma_f32_16x16x32_bf16 v[14:17], v[156:159], v[134:137], v[14:17]
	v_mfma_f32_16x16x32_bf16 v[10:13], v[156:159], v[138:141], v[10:13]
	v_mfma_f32_16x16x32_bf16 v[6:9], v[156:159], v[144:147], v[6:9]
	v_mfma_f32_16x16x32_bf16 v[2:5], v[156:159], v[148:151], v[2:5]
	ds_read_b128 v[134:137], v176 offset:0x1000
	ds_read_b128 v[236:239], v176 offset:0x2800
	s_waitcnt lgkmcnt(3)
	v_mfma_f32_16x16x32_bf16 v[126:129], v[172:175], v[160:163], v[126:129]
	v_mfma_f32_16x16x32_bf16 v[122:125], v[172:175], v[164:167], v[122:125]
	v_mfma_f32_16x16x32_bf16 v[118:121], v[172:175], v[168:171], v[118:121]
	v_mfma_f32_16x16x32_bf16 v[114:117], v[172:175], v[232:235], v[114:117]
	ds_read_b128 v[138:141], v176 offset:0x1800
	ds_read_b128 v[240:243], v176 offset:0x3000
	s_waitcnt lgkmcnt(4)
	v_mfma_f32_16x16x32_bf16 v[110:113], v[202:205], v[160:163], v[110:113]
	v_mfma_f32_16x16x32_bf16 v[106:109], v[202:205], v[164:167], v[106:109]
	v_mfma_f32_16x16x32_bf16 v[102:105], v[202:205], v[168:171], v[102:105]
	v_mfma_f32_16x16x32_bf16 v[98:101], v[202:205], v[232:235], v[98:101]
	ds_read_b128 v[144:147], v176 offset:0x2000
	ds_read_b128 v[244:247], v176 offset:0x3800
	s_waitcnt lgkmcnt(5)
	v_mfma_f32_16x16x32_bf16 v[94:97], v[134:137], v[160:163], v[94:97]
	v_mfma_f32_16x16x32_bf16 v[90:93], v[134:137], v[164:167], v[90:93]
	v_mfma_f32_16x16x32_bf16 v[86:89], v[134:137], v[168:171], v[86:89]
	v_mfma_f32_16x16x32_bf16 v[82:85], v[134:137], v[232:235], v[82:85]
	s_waitcnt lgkmcnt(3)
	v_mfma_f32_16x16x32_bf16 v[78:81], v[138:141], v[160:163], v[78:81]
	v_mfma_f32_16x16x32_bf16 v[74:77], v[138:141], v[164:167], v[74:77]
	v_mfma_f32_16x16x32_bf16 v[70:73], v[138:141], v[168:171], v[70:73]
	v_mfma_f32_16x16x32_bf16 v[66:69], v[138:141], v[232:235], v[66:69]
	s_waitcnt lgkmcnt(1)
	v_mfma_f32_16x16x32_bf16 v[62:65], v[144:147], v[160:163], v[62:65]
	v_mfma_f32_16x16x32_bf16 v[58:61], v[144:147], v[164:167], v[58:61]
	v_mfma_f32_16x16x32_bf16 v[54:57], v[144:147], v[168:171], v[54:57]
	v_mfma_f32_16x16x32_bf16 v[50:53], v[144:147], v[232:235], v[50:53]
	s_waitcnt lgkmcnt(0)
	s_waitcnt vmcnt(0)
	s_add_i32 s44, s44, 0x10000
	s_addk_i32 s45, 0x80
	s_add_i32 s41, s41, 1
	s_and_b32 s2, s44, 0x10000
	s_cmp_ge_u32 s41, s24
	s_barrier
	s_cbranch_scc0 .Lrot1_top_l
.Lrot1_top_n:
	v_add_u32_e32 v228, s2, v143
	v_add_u32_e32 v229, s2, v133
	ds_read_b128 v[134:137], v229 offset:0
	ds_read_b128 v[138:141], v229 offset:0x800
	ds_read_b128 v[144:147], v229 offset:0x1000
	ds_read_b128 v[148:151], v229 offset:0x1800
	ds_read_b128 v[152:155], v228 offset:0
	ds_read_b128 v[156:159], v228 offset:0x800
	v_mfma_f32_16x16x32_bf16 v[46:49], v[236:239], v[160:163], v[46:49]
	v_mfma_f32_16x16x32_bf16 v[42:45], v[236:239], v[164:167], v[42:45]
	v_mfma_f32_16x16x32_bf16 v[38:41], v[236:239], v[168:171], v[38:41]
	v_mfma_f32_16x16x32_bf16 v[34:37], v[236:239], v[232:235], v[34:37]
	v_mfma_f32_16x16x32_bf16 v[30:33], v[240:243], v[160:163], v[30:33]
	v_mfma_f32_16x16x32_bf16 v[26:29], v[240:243], v[164:167], v[26:29]
	v_mfma_f32_16x16x32_bf16 v[22:25], v[240:243], v[168:171], v[22:25]
	v_mfma_f32_16x16x32_bf16 v[18:21], v[240:243], v[232:235], v[18:21]
	v_mfma_f32_16x16x32_bf16 v[14:17], v[244:247], v[160:163], v[14:17]
	v_mfma_f32_16x16x32_bf16 v[10:13], v[244:247], v[164:167], v[10:13]
	v_mfma_f32_16x16x32_bf16 v[6:9], v[244:247], v[168:171], v[6:9]
	v_mfma_f32_16x16x32_bf16 v[2:5], v[244:247], v[232:235], v[2:5]
	ds_read_b128 v[160:163], v228 offset:0x1000
	v_xor_b32_e32 v176, 64, v228
	s_waitcnt lgkmcnt(2)
	v_mfma_f32_16x16x32_bf16 v[126:129], v[152:155], v[134:137], v[126:129]
	v_mfma_f32_16x16x32_bf16 v[122:125], v[152:155], v[138:141], v[122:125]
	v_mfma_f32_16x16x32_bf16 v[118:121], v[152:155], v[144:147], v[118:121]
	v_mfma_f32_16x16x32_bf16 v[114:117], v[152:155], v[148:151], v[114:117]
	ds_read_b128 v[152:155], v228 offset:0x1800
	s_waitcnt lgkmcnt(2)
	v_mfma_f32_16x16x32_bf16 v[110:113], v[156:159], v[134:137], v[110:113]
	v_mfma_f32_16x16x32_bf16 v[106:109], v[156:159], v[138:141], v[106:109]
	v_mfma_f32_16x16x32_bf16 v[102:105], v[156:159], v[144:147], v[102:105]
	v_mfma_f32_16x16x32_bf16 v[98:101], v[156:159], v[148:151], v[98:101]
	ds_read_b128 v[156:159], v228 offset:0x2000
	s_waitcnt lgkmcnt(2)
	v_mfma_f32_16x16x32_bf16 v[94:97], v[160:163], v[134:137], v[94:97]
	v_mfma_f32_16x16x32_bf16 v[90:93], v[160:163], v[138:141], v[90:93]
	v_mfma_f32_16x16x32_bf16 v[86:89], v[160:163], v[144:147], v[86:89]
	v_mfma_f32_16x16x32_bf16 v[82:85], v[160:163], v[148:151], v[82:85]
	ds_read_b128 v[160:163], v228 offset:0x2800
	s_waitcnt lgkmcnt(2)
	v_mfma_f32_16x16x32_bf16 v[78:81], v[152:155], v[134:137], v[78:81]
	v_mfma_f32_16x16x32_bf16 v[74:77], v[152:155], v[138:141], v[74:77]
	v_mfma_f32_16x16x32_bf16 v[70:73], v[152:155], v[144:147], v[70:73]
	v_mfma_f32_16x16x32_bf16 v[66:69], v[152:155], v[148:151], v[66:69]
	ds_read_b128 v[152:155], v228 offset:0x3000
	s_waitcnt lgkmcnt(2)
	v_mfma_f32_16x16x32_bf16 v[62:65], v[156:159], v[134:137], v[62:65]
	v_mfma_f32_16x16x32_bf16 v[58:61], v[156:159], v[138:141], v[58:61]
	v_mfma_f32_16x16x32_bf16 v[54:57], v[156:159], v[144:147], v[54:57]
	v_mfma_f32_16x16x32_bf16 v[50:53], v[156:159], v[148:151], v[50:53]
	ds_read_b128 v[156:159], v228 offset:0x3800
	s_waitcnt lgkmcnt(2)
	v_xor_b32_e32 v0, 64, v229
	v_mfma_f32_16x16x32_bf16 v[46:49], v[160:163], v[134:137], v[46:49]
	v_mfma_f32_16x16x32_bf16 v[42:45], v[160:163], v[138:141], v[42:45]
	v_mfma_f32_16x16x32_bf16 v[38:41], v[160:163], v[144:147], v[38:41]
	v_mfma_f32_16x16x32_bf16 v[34:37], v[160:163], v[148:151], v[34:37]
	ds_read_b128 v[160:163], v0 offset:0
	ds_read_b128 v[164:167], v0 offset:0x800
	ds_read_b128 v[168:171], v0 offset:0x1000
	s_waitcnt lgkmcnt(4)
	v_mfma_f32_16x16x32_bf16 v[30:33], v[152:155], v[134:137], v[30:33]
	v_mfma_f32_16x16x32_bf16 v[26:29], v[152:155], v[138:141], v[26:29]
	v_mfma_f32_16x16x32_bf16 v[22:25], v[152:155], v[144:147], v[22:25]
	v_mfma_f32_16x16x32_bf16 v[18:21], v[152:155], v[148:151], v[18:21]
	ds_read_b128 v[232:235], v0 offset:0x1800
	ds_read_b128 v[172:175], v176 offset:0
	ds_read_b128 v[202:205], v176 offset:0x800
	s_waitcnt lgkmcnt(6)
	v_mfma_f32_16x16x32_bf16 v[14:17], v[156:159], v[134:137], v[14:17]
	v_mfma_f32_16x16x32_bf16 v[10:13], v[156:159], v[138:141], v[10:13]
	v_mfma_f32_16x16x32_bf16 v[6:9], v[156:159], v[144:147], v[6:9]
	v_mfma_f32_16x16x32_bf16 v[2:5], v[156:159], v[148:151], v[2:5]
	ds_read_b128 v[134:137], v176 offset:0x1000
	ds_read_b128 v[236:239], v176 offset:0x2800
	s_waitcnt lgkmcnt(3)
	v_mfma_f32_16x16x32_bf16 v[126:129], v[172:175], v[160:163], v[126:129]
	v_mfma_f32_16x16x32_bf16 v[122:125], v[172:175], v[164:167], v[122:125]
	v_mfma_f32_16x16x32_bf16 v[118:121], v[172:175], v[168:171], v[118:121]
	v_mfma_f32_16x16x32_bf16 v[114:117], v[172:175], v[232:235], v[114:117]
	ds_read_b128 v[138:141], v176 offset:0x1800
	ds_read_b128 v[240:243], v176 offset:0x3000
	s_waitcnt lgkmcnt(4)
	v_mfma_f32_16x16x32_bf16 v[110:113], v[202:205], v[160:163], v[110:113]
	v_mfma_f32_16x16x32_bf16 v[106:109], v[202:205], v[164:167], v[106:109]
	v_mfma_f32_16x16x32_bf16 v[102:105], v[202:205], v[168:171], v[102:105]
	v_mfma_f32_16x16x32_bf16 v[98:101], v[202:205], v[232:235], v[98:101]
	ds_read_b128 v[144:147], v176 offset:0x2000
	ds_read_b128 v[244:247], v176 offset:0x3800
	s_waitcnt lgkmcnt(5)
	v_mfma_f32_16x16x32_bf16 v[94:97], v[134:137], v[160:163], v[94:97]
	v_mfma_f32_16x16x32_bf16 v[90:93], v[134:137], v[164:167], v[90:93]
	v_mfma_f32_16x16x32_bf16 v[86:89], v[134:137], v[168:171], v[86:89]
	v_mfma_f32_16x16x32_bf16 v[82:85], v[134:137], v[232:235], v[82:85]
	s_waitcnt lgkmcnt(3)
	v_mfma_f32_16x16x32_bf16 v[78:81], v[138:141], v[160:163], v[78:81]
	v_mfma_f32_16x16x32_bf16 v[74:77], v[138:141], v[164:167], v[74:77]
	v_mfma_f32_16x16x32_bf16 v[70:73], v[138:141], v[168:171], v[70:73]
	v_mfma_f32_16x16x32_bf16 v[66:69], v[138:141], v[232:235], v[66:69]
	s_waitcnt lgkmcnt(1)
	v_mfma_f32_16x16x32_bf16 v[62:65], v[144:147], v[160:163], v[62:65]
	v_mfma_f32_16x16x32_bf16 v[58:61], v[144:147], v[164:167], v[58:61]
	v_mfma_f32_16x16x32_bf16 v[54:57], v[144:147], v[168:171], v[54:57]
	v_mfma_f32_16x16x32_bf16 v[50:53], v[144:147], v[232:235], v[50:53]
	s_waitcnt lgkmcnt(0)
	s_add_i32 s44, s44, 0x10000
	s_addk_i32 s45, 0x80
	s_add_i32 s41, s41, 1
	s_barrier
	v_mfma_f32_16x16x32_bf16 v[46:49], v[236:239], v[160:163], v[46:49]
	v_mfma_f32_16x16x32_bf16 v[42:45], v[236:239], v[164:167], v[42:45]
	v_mfma_f32_16x16x32_bf16 v[38:41], v[236:239], v[168:171], v[38:41]
	v_mfma_f32_16x16x32_bf16 v[34:37], v[236:239], v[232:235], v[34:37]
	v_mfma_f32_16x16x32_bf16 v[30:33], v[240:243], v[160:163], v[30:33]
	v_mfma_f32_16x16x32_bf16 v[26:29], v[240:243], v[164:167], v[26:29]
	v_mfma_f32_16x16x32_bf16 v[22:25], v[240:243], v[168:171], v[22:25]
	v_mfma_f32_16x16x32_bf16 v[18:21], v[240:243], v[232:235], v[18:21]
	v_mfma_f32_16x16x32_bf16 v[14:17], v[244:247], v[160:163], v[14:17]
	v_mfma_f32_16x16x32_bf16 v[10:13], v[244:247], v[164:167], v[10:13]
	v_mfma_f32_16x16x32_bf16 v[6:9], v[244:247], v[168:171], v[6:9]
	v_mfma_f32_16x16x32_bf16 v[2:5], v[244:247], v[232:235], v[2:5]
	s_nop 7
	s_nop 7
	s_nop 3

.LBB0_429:
	s_cmp_eq_u32 s15, 0x60800
	s_mov_b32 s2, 0x10000
	s_and_b32 s2, s13, 0x10000
	s_xor_b32 s10, s2, 0x10000
	s_add_i32 s35, s22, s10
	s_add_i32 s36, s15, 0xfffa0000
	s_add_i32 s37, s35, 0x8000
	s_mov_b32 s10, s66
	s_mov_b32 s11, s67
	s_waitcnt lgkmcnt(0)
	v_add_u32_e32 v228, s2, v207
	v_add_u32_e32 v229, s2, v204
	ds_read_b128 v[50:53], v229 offset:0
	ds_read_b128 v[54:57], v229 offset:0x800
	ds_read_b128 v[58:61], v229 offset:0x1000
	ds_read_b128 v[78:81], v229 offset:0x1800
	ds_read_b128 v[98:101], v228 offset:0
	ds_read_b128 v[118:121], v228 offset:0x800
	s_mov_b32 m0, s35
	s_nop 0
	buffer_load_dwordx4 v201, s[64:67], s36 offen lds
	s_mov_b32 m0, s37
	s_nop 0
	buffer_load_dwordx4 v248, s[8:11], s36 offen lds
	s_add_i32 m0, s35, 0x2000
	s_add_i32 s36, s15, 0xfffc0000
	buffer_load_dwordx4 v201, s[64:67], s36 offen lds
	s_add_i32 m0, s35, 0xa000
	s_nop 0
	buffer_load_dwordx4 v248, s[8:11], s36 offen lds
	s_add_i32 m0, s35, 0x4000
	s_add_i32 s36, s15, 0xfffe0000
	buffer_load_dwordx4 v201, s[64:67], s36 offen lds
	ds_read_b128 v[138:141], v228 offset:0x1000
	v_xor_b32_e32 v208, 64, v228
	s_waitcnt lgkmcnt(2)
	v_mfma_f32_16x16x32_bf16 v[150:153], v[98:101], v[50:53], 0
	v_mfma_f32_16x16x32_bf16 v[154:157], v[98:101], v[54:57], 0
	v_mfma_f32_16x16x32_bf16 v[142:145], v[98:101], v[58:61], 0
	v_mfma_f32_16x16x32_bf16 v[98:101], v[98:101], v[78:81], 0
	s_add_i32 m0, s35, 0xc000
	s_nop 0
	buffer_load_dwordx4 v248, s[8:11], s36 offen lds
	ds_read_b128 v[146:149], v228 offset:0x1800
	s_waitcnt lgkmcnt(2)
	v_mfma_f32_16x16x32_bf16 v[130:133], v[118:121], v[50:53], 0
	v_mfma_f32_16x16x32_bf16 v[134:137], v[118:121], v[54:57], 0
	v_mfma_f32_16x16x32_bf16 v[122:125], v[118:121], v[58:61], 0
	v_mfma_f32_16x16x32_bf16 v[118:121], v[118:121], v[78:81], 0
	s_add_i32 m0, s35, 0x6000
	s_nop 0
	buffer_load_dwordx4 v201, s[64:67], s15 offen lds
	ds_read_b128 v[126:129], v228 offset:0x2000
	s_waitcnt lgkmcnt(2)
	v_mfma_f32_16x16x32_bf16 v[110:113], v[138:141], v[50:53], 0
	v_mfma_f32_16x16x32_bf16 v[114:117], v[138:141], v[54:57], 0
	v_mfma_f32_16x16x32_bf16 v[102:105], v[138:141], v[58:61], 0
	v_mfma_f32_16x16x32_bf16 v[106:109], v[138:141], v[78:81], 0
	s_add_i32 m0, s35, 0xe000
	s_nop 0
	buffer_load_dwordx4 v248, s[8:11], s15 offen lds
	ds_read_b128 v[138:141], v228 offset:0x2800
	s_waitcnt lgkmcnt(2)
	v_mfma_f32_16x16x32_bf16 v[90:93], v[146:149], v[50:53], 0
	v_mfma_f32_16x16x32_bf16 v[94:97], v[146:149], v[54:57], 0
	v_mfma_f32_16x16x32_bf16 v[82:85], v[146:149], v[58:61], 0
	v_mfma_f32_16x16x32_bf16 v[86:89], v[146:149], v[78:81], 0
	ds_read_b128 v[146:149], v228 offset:0x3000
	s_waitcnt lgkmcnt(2)
	v_mfma_f32_16x16x32_bf16 v[70:73], v[126:129], v[50:53], 0
	v_mfma_f32_16x16x32_bf16 v[74:77], v[126:129], v[54:57], 0
	v_mfma_f32_16x16x32_bf16 v[62:65], v[126:129], v[58:61], 0
	v_mfma_f32_16x16x32_bf16 v[66:69], v[126:129], v[78:81], 0
	ds_read_b128 v[126:129], v228 offset:0x3800
	s_waitcnt lgkmcnt(2)
	v_xor_b32_e32 v166, 64, v229
	v_mfma_f32_16x16x32_bf16 v[42:45], v[138:141], v[50:53], 0
	v_mfma_f32_16x16x32_bf16 v[46:49], v[138:141], v[54:57], 0
	v_mfma_f32_16x16x32_bf16 v[34:37], v[138:141], v[58:61], 0
	v_mfma_f32_16x16x32_bf16 v[38:41], v[138:141], v[78:81], 0
	ds_read_b128 v[138:141], v166 offset:0
	ds_read_b128 v[158:161], v166 offset:0x800
	ds_read_b128 v[162:165], v166 offset:0x1000
	s_waitcnt lgkmcnt(4)
	v_mfma_f32_16x16x32_bf16 v[26:29], v[146:149], v[50:53], 0
	v_mfma_f32_16x16x32_bf16 v[30:33], v[146:149], v[54:57], 0
	v_mfma_f32_16x16x32_bf16 v[18:21], v[146:149], v[58:61], 0
	v_mfma_f32_16x16x32_bf16 v[22:25], v[146:149], v[78:81], 0
	ds_read_b128 v[166:169], v166 offset:0x1800
	ds_read_b128 v[146:149], v208 offset:0
	ds_read_b128 v[174:177], v208 offset:0x800
	s_waitcnt lgkmcnt(6)
	v_mfma_f32_16x16x32_bf16 v[10:13], v[126:129], v[50:53], 0
	v_mfma_f32_16x16x32_bf16 v[14:17], v[126:129], v[54:57], 0
	v_mfma_f32_16x16x32_bf16 v[2:5], v[126:129], v[58:61], 0
	v_mfma_f32_16x16x32_bf16 v[6:9], v[126:129], v[78:81], 0
	ds_read_b128 v[50:53], v208 offset:0x1000
	ds_read_b128 v[232:235], v208 offset:0x2800
	s_waitcnt lgkmcnt(3)
	v_mfma_f32_16x16x32_bf16 v[150:153], v[146:149], v[138:141], v[150:153]
	v_mfma_f32_16x16x32_bf16 v[154:157], v[146:149], v[158:161], v[154:157]
	v_mfma_f32_16x16x32_bf16 v[142:145], v[146:149], v[162:165], v[142:145]
	v_mfma_f32_16x16x32_bf16 v[146:149], v[146:149], v[166:169], v[98:101]
	ds_read_b128 v[54:57], v208 offset:0x1800
	ds_read_b128 v[236:239], v208 offset:0x3000
	s_waitcnt lgkmcnt(4)
	v_mfma_f32_16x16x32_bf16 v[130:133], v[174:177], v[138:141], v[130:133]
	v_mfma_f32_16x16x32_bf16 v[134:137], v[174:177], v[158:161], v[134:137]
	v_mfma_f32_16x16x32_bf16 v[122:125], v[174:177], v[162:165], v[122:125]
	v_mfma_f32_16x16x32_bf16 v[126:129], v[174:177], v[166:169], v[118:121]
	ds_read_b128 v[58:61], v208 offset:0x2000
	ds_read_b128 v[240:243], v208 offset:0x3800
	s_waitcnt lgkmcnt(5)
	v_mfma_f32_16x16x32_bf16 v[110:113], v[50:53], v[138:141], v[110:113]
	v_mfma_f32_16x16x32_bf16 v[114:117], v[50:53], v[158:161], v[114:117]
	v_mfma_f32_16x16x32_bf16 v[102:105], v[50:53], v[162:165], v[102:105]
	v_mfma_f32_16x16x32_bf16 v[106:109], v[50:53], v[166:169], v[106:109]
	s_waitcnt lgkmcnt(3)
	v_mfma_f32_16x16x32_bf16 v[90:93], v[54:57], v[138:141], v[90:93]
	v_mfma_f32_16x16x32_bf16 v[94:97], v[54:57], v[158:161], v[94:97]
	v_mfma_f32_16x16x32_bf16 v[82:85], v[54:57], v[162:165], v[82:85]
	v_mfma_f32_16x16x32_bf16 v[86:89], v[54:57], v[166:169], v[86:89]
	s_waitcnt lgkmcnt(1)
	v_mfma_f32_16x16x32_bf16 v[70:73], v[58:61], v[138:141], v[70:73]
	v_mfma_f32_16x16x32_bf16 v[74:77], v[58:61], v[158:161], v[74:77]
	v_mfma_f32_16x16x32_bf16 v[62:65], v[58:61], v[162:165], v[62:65]
	v_mfma_f32_16x16x32_bf16 v[66:69], v[58:61], v[166:169], v[66:69]
	s_waitcnt lgkmcnt(0)
	s_waitcnt vmcnt(0)
	s_add_i32 s13, s13, 0x10000
	s_addk_i32 s15, 0x80
	s_cmp_eq_u32 s15, 0x60800
	s_mov_b32 s2, 0x10000
	s_barrier
	s_cbranch_scc0 .Lrot0_top_l
	s_branch .Lrot0_top_n
.Lrot0_top_l:
	s_and_b32 s2, s13, 0x10000
	s_xor_b32 s10, s2, 0x10000
	s_add_i32 s35, s22, s10
	s_add_i32 s36, s15, 0xfffa0000
	s_add_i32 s37, s35, 0x8000
	s_mov_b32 s10, s66
	s_mov_b32 s11, s67
	v_add_u32_e32 v228, s2, v207
	v_add_u32_e32 v229, s2, v204
	ds_read_b128 v[50:53], v229 offset:0
	ds_read_b128 v[54:57], v229 offset:0x800
	ds_read_b128 v[58:61], v229 offset:0x1000
	ds_read_b128 v[78:81], v229 offset:0x1800
	ds_read_b128 v[98:101], v228 offset:0
	ds_read_b128 v[118:121], v228 offset:0x800
	s_mov_b32 m0, s35
	s_nop 0
	buffer_load_dwordx4 v201, s[64:67], s36 offen lds
	s_mov_b32 m0, s37
	s_nop 0
	buffer_load_dwordx4 v248, s[8:11], s36 offen lds
	v_mfma_f32_16x16x32_bf16 v[42:45], v[232:235], v[138:141], v[42:45]
	v_mfma_f32_16x16x32_bf16 v[46:49], v[232:235], v[158:161], v[46:49]
	v_mfma_f32_16x16x32_bf16 v[34:37], v[232:235], v[162:165], v[34:37]
	v_mfma_f32_16x16x32_bf16 v[38:41], v[232:235], v[166:169], v[38:41]
	s_add_i32 m0, s35, 0x2000
	s_add_i32 s36, s15, 0xfffc0000
	buffer_load_dwordx4 v201, s[64:67], s36 offen lds
	v_mfma_f32_16x16x32_bf16 v[26:29], v[236:239], v[138:141], v[26:29]
	v_mfma_f32_16x16x32_bf16 v[30:33], v[236:239], v[158:161], v[30:33]
	v_mfma_f32_16x16x32_bf16 v[18:21], v[236:239], v[162:165], v[18:21]
	v_mfma_f32_16x16x32_bf16 v[22:25], v[236:239], v[166:169], v[22:25]
	s_add_i32 m0, s35, 0xa000
	s_nop 0
	buffer_load_dwordx4 v248, s[8:11], s36 offen lds
	v_mfma_f32_16x16x32_bf16 v[10:13], v[240:243], v[138:141], v[10:13]
	v_mfma_f32_16x16x32_bf16 v[14:17], v[240:243], v[158:161], v[14:17]
	v_mfma_f32_16x16x32_bf16 v[2:5], v[240:243], v[162:165], v[2:5]
	v_mfma_f32_16x16x32_bf16 v[6:9], v[240:243], v[166:169], v[6:9]
	s_add_i32 m0, s35, 0x4000
	s_add_i32 s36, s15, 0xfffe0000
	buffer_load_dwordx4 v201, s[64:67], s36 offen lds
	ds_read_b128 v[138:141], v228 offset:0x1000
	v_xor_b32_e32 v208, 64, v228
.Lrot0_mid_l:
	s_waitcnt lgkmcnt(2)
	v_mfma_f32_16x16x32_bf16 v[150:153], v[98:101], v[50:53], v[150:153]
	v_mfma_f32_16x16x32_bf16 v[154:157], v[98:101], v[54:57], v[154:157]
	v_mfma_f32_16x16x32_bf16 v[142:145], v[98:101], v[58:61], v[142:145]
	v_mfma_f32_16x16x32_bf16 v[98:101], v[98:101], v[78:81], v[146:149]
	s_add_i32 m0, s35, 0xc000
	s_nop 0
	buffer_load_dwordx4 v248, s[8:11], s36 offen lds
	ds_read_b128 v[146:149], v228 offset:0x1800
	s_waitcnt lgkmcnt(2)
	v_mfma_f32_16x16x32_bf16 v[130:133], v[118:121], v[50:53], v[130:133]
	v_mfma_f32_16x16x32_bf16 v[134:137], v[118:121], v[54:57], v[134:137]
	v_mfma_f32_16x16x32_bf16 v[122:125], v[118:121], v[58:61], v[122:125]
	v_mfma_f32_16x16x32_bf16 v[118:121], v[118:121], v[78:81], v[126:129]
	s_add_i32 m0, s35, 0x6000
	s_nop 0
	buffer_load_dwordx4 v201, s[64:67], s15 offen lds
	ds_read_b128 v[126:129], v228 offset:0x2000
	s_waitcnt lgkmcnt(2)
	v_mfma_f32_16x16x32_bf16 v[110:113], v[138:141], v[50:53], v[110:113]
	v_mfma_f32_16x16x32_bf16 v[114:117], v[138:141], v[54:57], v[114:117]
	v_mfma_f32_16x16x32_bf16 v[102:105], v[138:141], v[58:61], v[102:105]
	v_mfma_f32_16x16x32_bf16 v[106:109], v[138:141], v[78:81], v[106:109]
	s_add_i32 m0, s35, 0xe000
	s_nop 0
	buffer_load_dwordx4 v248, s[8:11], s15 offen lds
	ds_read_b128 v[138:141], v228 offset:0x2800
	s_waitcnt lgkmcnt(2)
	v_mfma_f32_16x16x32_bf16 v[90:93], v[146:149], v[50:53], v[90:93]
	v_mfma_f32_16x16x32_bf16 v[94:97], v[146:149], v[54:57], v[94:97]
	v_mfma_f32_16x16x32_bf16 v[82:85], v[146:149], v[58:61], v[82:85]
	v_mfma_f32_16x16x32_bf16 v[86:89], v[146:149], v[78:81], v[86:89]
	ds_read_b128 v[146:149], v228 offset:0x3000
	s_waitcnt lgkmcnt(2)
	v_mfma_f32_16x16x32_bf16 v[70:73], v[126:129], v[50:53], v[70:73]
	v_mfma_f32_16x16x32_bf16 v[74:77], v[126:129], v[54:57], v[74:77]
	v_mfma_f32_16x16x32_bf16 v[62:65], v[126:129], v[58:61], v[62:65]
	v_mfma_f32_16x16x32_bf16 v[66:69], v[126:129], v[78:81], v[66:69]
	ds_read_b128 v[126:129], v228 offset:0x3800
	s_waitcnt lgkmcnt(2)
	v_xor_b32_e32 v166, 64, v229
	v_mfma_f32_16x16x32_bf16 v[42:45], v[138:141], v[50:53], v[42:45]
	v_mfma_f32_16x16x32_bf16 v[46:49], v[138:141], v[54:57], v[46:49]
	v_mfma_f32_16x16x32_bf16 v[34:37], v[138:141], v[58:61], v[34:37]
	v_mfma_f32_16x16x32_bf16 v[38:41], v[138:141], v[78:81], v[38:41]
	ds_read_b128 v[138:141], v166 offset:0
	ds_read_b128 v[158:161], v166 offset:0x800
	ds_read_b128 v[162:165], v166 offset:0x1000
	s_waitcnt lgkmcnt(4)
	v_mfma_f32_16x16x32_bf16 v[26:29], v[146:149], v[50:53], v[26:29]
	v_mfma_f32_16x16x32_bf16 v[30:33], v[146:149], v[54:57], v[30:33]
	v_mfma_f32_16x16x32_bf16 v[18:21], v[146:149], v[58:61], v[18:21]
	v_mfma_f32_16x16x32_bf16 v[22:25], v[146:149], v[78:81], v[22:25]
	ds_read_b128 v[166:169], v166 offset:0x1800
	ds_read_b128 v[146:149], v208 offset:0
	ds_read_b128 v[174:177], v208 offset:0x800
	s_waitcnt lgkmcnt(6)
	v_mfma_f32_16x16x32_bf16 v[10:13], v[126:129], v[50:53], v[10:13]
	v_mfma_f32_16x16x32_bf16 v[14:17], v[126:129], v[54:57], v[14:17]
	v_mfma_f32_16x16x32_bf16 v[2:5], v[126:129], v[58:61], v[2:5]
	v_mfma_f32_16x16x32_bf16 v[6:9], v[126:129], v[78:81], v[6:9]
	ds_read_b128 v[50:53], v208 offset:0x1000
	ds_read_b128 v[232:235], v208 offset:0x2800
	s_waitcnt lgkmcnt(3)
	v_mfma_f32_16x16x32_bf16 v[150:153], v[146:149], v[138:141], v[150:153]
	v_mfma_f32_16x16x32_bf16 v[154:157], v[146:149], v[158:161], v[154:157]
	v_mfma_f32_16x16x32_bf16 v[142:145], v[146:149], v[162:165], v[142:145]
	v_mfma_f32_16x16x32_bf16 v[146:149], v[146:149], v[166:169], v[98:101]
	ds_read_b128 v[54:57], v208 offset:0x1800
	ds_read_b128 v[236:239], v208 offset:0x3000
	s_waitcnt lgkmcnt(4)
	v_mfma_f32_16x16x32_bf16 v[130:133], v[174:177], v[138:141], v[130:133]
	v_mfma_f32_16x16x32_bf16 v[134:137], v[174:177], v[158:161], v[134:137]
	v_mfma_f32_16x16x32_bf16 v[122:125], v[174:177], v[162:165], v[122:125]
	v_mfma_f32_16x16x32_bf16 v[126:129], v[174:177], v[166:169], v[118:121]
	ds_read_b128 v[58:61], v208 offset:0x2000
	ds_read_b128 v[240:243], v208 offset:0x3800
	s_waitcnt lgkmcnt(5)
	v_mfma_f32_16x16x32_bf16 v[110:113], v[50:53], v[138:141], v[110:113]
	v_mfma_f32_16x16x32_bf16 v[114:117], v[50:53], v[158:161], v[114:117]
	v_mfma_f32_16x16x32_bf16 v[102:105], v[50:53], v[162:165], v[102:105]
	v_mfma_f32_16x16x32_bf16 v[106:109], v[50:53], v[166:169], v[106:109]
	s_waitcnt lgkmcnt(3)
	v_mfma_f32_16x16x32_bf16 v[90:93], v[54:57], v[138:141], v[90:93]
	v_mfma_f32_16x16x32_bf16 v[94:97], v[54:57], v[158:161], v[94:97]
	v_mfma_f32_16x16x32_bf16 v[82:85], v[54:57], v[162:165], v[82:85]
	v_mfma_f32_16x16x32_bf16 v[86:89], v[54:57], v[166:169], v[86:89]
	s_waitcnt lgkmcnt(1)
	v_mfma_f32_16x16x32_bf16 v[70:73], v[58:61], v[138:141], v[70:73]
	v_mfma_f32_16x16x32_bf16 v[74:77], v[58:61], v[158:161], v[74:77]
	v_mfma_f32_16x16x32_bf16 v[62:65], v[58:61], v[162:165], v[62:65]
	v_mfma_f32_16x16x32_bf16 v[66:69], v[58:61], v[166:169], v[66:69]
	s_waitcnt lgkmcnt(0)
	s_waitcnt vmcnt(0)
	s_add_i32 s13, s13, 0x10000
	s_addk_i32 s15, 0x80
	s_cmp_eq_u32 s15, 0x60800
	s_mov_b32 s2, 0x10000
	s_barrier
	s_cbranch_scc0 .Lrot0_top_l
.Lrot0_top_n:
	v_add_u32_e32 v228, s2, v207
	v_add_u32_e32 v229, s2, v204
	ds_read_b128 v[50:53], v229 offset:0
	ds_read_b128 v[54:57], v229 offset:0x800
	ds_read_b128 v[58:61], v229 offset:0x1000
	ds_read_b128 v[78:81], v229 offset:0x1800
	ds_read_b128 v[98:101], v228 offset:0
	ds_read_b128 v[118:121], v228 offset:0x800
	v_mfma_f32_16x16x32_bf16 v[42:45], v[232:235], v[138:141], v[42:45]
	v_mfma_f32_16x16x32_bf16 v[46:49], v[232:235], v[158:161], v[46:49]
	v_mfma_f32_16x16x32_bf16 v[34:37], v[232:235], v[162:165], v[34:37]
	v_mfma_f32_16x16x32_bf16 v[38:41], v[232:235], v[166:169], v[38:41]
	v_mfma_f32_16x16x32_bf16 v[26:29], v[236:239], v[138:141], v[26:29]
	v_mfma_f32_16x16x32_bf16 v[30:33], v[236:239], v[158:161], v[30:33]
	v_mfma_f32_16x16x32_bf16 v[18:21], v[236:239], v[162:165], v[18:21]
	v_mfma_f32_16x16x32_bf16 v[22:25], v[236:239], v[166:169], v[22:25]
	v_mfma_f32_16x16x32_bf16 v[10:13], v[240:243], v[138:141], v[10:13]
	v_mfma_f32_16x16x32_bf16 v[14:17], v[240:243], v[158:161], v[14:17]
	v_mfma_f32_16x16x32_bf16 v[2:5], v[240:243], v[162:165], v[2:5]
	v_mfma_f32_16x16x32_bf16 v[6:9], v[240:243], v[166:169], v[6:9]
	ds_read_b128 v[138:141], v228 offset:0x1000
	v_xor_b32_e32 v208, 64, v228
	s_waitcnt lgkmcnt(2)
	v_mfma_f32_16x16x32_bf16 v[150:153], v[98:101], v[50:53], v[150:153]
	v_mfma_f32_16x16x32_bf16 v[154:157], v[98:101], v[54:57], v[154:157]
	v_mfma_f32_16x16x32_bf16 v[142:145], v[98:101], v[58:61], v[142:145]
	v_mfma_f32_16x16x32_bf16 v[98:101], v[98:101], v[78:81], v[146:149]
	ds_read_b128 v[146:149], v228 offset:0x1800
	s_waitcnt lgkmcnt(2)
	v_mfma_f32_16x16x32_bf16 v[130:133], v[118:121], v[50:53], v[130:133]
	v_mfma_f32_16x16x32_bf16 v[134:137], v[118:121], v[54:57], v[134:137]
	v_mfma_f32_16x16x32_bf16 v[122:125], v[118:121], v[58:61], v[122:125]
	v_mfma_f32_16x16x32_bf16 v[118:121], v[118:121], v[78:81], v[126:129]
	ds_read_b128 v[126:129], v228 offset:0x2000
	s_waitcnt lgkmcnt(2)
	v_mfma_f32_16x16x32_bf16 v[110:113], v[138:141], v[50:53], v[110:113]
	v_mfma_f32_16x16x32_bf16 v[114:117], v[138:141], v[54:57], v[114:117]
	v_mfma_f32_16x16x32_bf16 v[102:105], v[138:141], v[58:61], v[102:105]
	v_mfma_f32_16x16x32_bf16 v[106:109], v[138:141], v[78:81], v[106:109]
	ds_read_b128 v[138:141], v228 offset:0x2800
	s_waitcnt lgkmcnt(2)
	v_mfma_f32_16x16x32_bf16 v[90:93], v[146:149], v[50:53], v[90:93]
	v_mfma_f32_16x16x32_bf16 v[94:97], v[146:149], v[54:57], v[94:97]
	v_mfma_f32_16x16x32_bf16 v[82:85], v[146:149], v[58:61], v[82:85]
	v_mfma_f32_16x16x32_bf16 v[86:89], v[146:149], v[78:81], v[86:89]
	ds_read_b128 v[146:149], v228 offset:0x3000
	s_waitcnt lgkmcnt(2)
	v_mfma_f32_16x16x32_bf16 v[70:73], v[126:129], v[50:53], v[70:73]
	v_mfma_f32_16x16x32_bf16 v[74:77], v[126:129], v[54:57], v[74:77]
	v_mfma_f32_16x16x32_bf16 v[62:65], v[126:129], v[58:61], v[62:65]
	v_mfma_f32_16x16x32_bf16 v[66:69], v[126:129], v[78:81], v[66:69]
	ds_read_b128 v[126:129], v228 offset:0x3800
	s_waitcnt lgkmcnt(2)
	v_xor_b32_e32 v166, 64, v229
	v_mfma_f32_16x16x32_bf16 v[42:45], v[138:141], v[50:53], v[42:45]
	v_mfma_f32_16x16x32_bf16 v[46:49], v[138:141], v[54:57], v[46:49]
	v_mfma_f32_16x16x32_bf16 v[34:37], v[138:141], v[58:61], v[34:37]
	v_mfma_f32_16x16x32_bf16 v[38:41], v[138:141], v[78:81], v[38:41]
	ds_read_b128 v[138:141], v166 offset:0
	ds_read_b128 v[158:161], v166 offset:0x800
	ds_read_b128 v[162:165], v166 offset:0x1000
	s_waitcnt lgkmcnt(4)
	v_mfma_f32_16x16x32_bf16 v[26:29], v[146:149], v[50:53], v[26:29]
	v_mfma_f32_16x16x32_bf16 v[30:33], v[146:149], v[54:57], v[30:33]
	v_mfma_f32_16x16x32_bf16 v[18:21], v[146:149], v[58:61], v[18:21]
	v_mfma_f32_16x16x32_bf16 v[22:25], v[146:149], v[78:81], v[22:25]
	ds_read_b128 v[166:169], v166 offset:0x1800
	ds_read_b128 v[146:149], v208 offset:0
	ds_read_b128 v[174:177], v208 offset:0x800
	s_waitcnt lgkmcnt(6)
	v_mfma_f32_16x16x32_bf16 v[10:13], v[126:129], v[50:53], v[10:13]
	v_mfma_f32_16x16x32_bf16 v[14:17], v[126:129], v[54:57], v[14:17]
	v_mfma_f32_16x16x32_bf16 v[2:5], v[126:129], v[58:61], v[2:5]
	v_mfma_f32_16x16x32_bf16 v[6:9], v[126:129], v[78:81], v[6:9]
	ds_read_b128 v[50:53], v208 offset:0x1000
	ds_read_b128 v[232:235], v208 offset:0x2800
	s_waitcnt lgkmcnt(3)
	v_mfma_f32_16x16x32_bf16 v[150:153], v[146:149], v[138:141], v[150:153]
	v_mfma_f32_16x16x32_bf16 v[154:157], v[146:149], v[158:161], v[154:157]
	v_mfma_f32_16x16x32_bf16 v[142:145], v[146:149], v[162:165], v[142:145]
	v_mfma_f32_16x16x32_bf16 v[146:149], v[146:149], v[166:169], v[98:101]
	ds_read_b128 v[54:57], v208 offset:0x1800
	ds_read_b128 v[236:239], v208 offset:0x3000
	s_waitcnt lgkmcnt(4)
	v_mfma_f32_16x16x32_bf16 v[130:133], v[174:177], v[138:141], v[130:133]
	v_mfma_f32_16x16x32_bf16 v[134:137], v[174:177], v[158:161], v[134:137]
	v_mfma_f32_16x16x32_bf16 v[122:125], v[174:177], v[162:165], v[122:125]
	v_mfma_f32_16x16x32_bf16 v[126:129], v[174:177], v[166:169], v[118:121]
	ds_read_b128 v[58:61], v208 offset:0x2000
	ds_read_b128 v[240:243], v208 offset:0x3800
	s_waitcnt lgkmcnt(5)
	v_mfma_f32_16x16x32_bf16 v[110:113], v[50:53], v[138:141], v[110:113]
	v_mfma_f32_16x16x32_bf16 v[114:117], v[50:53], v[158:161], v[114:117]
	v_mfma_f32_16x16x32_bf16 v[102:105], v[50:53], v[162:165], v[102:105]
	v_mfma_f32_16x16x32_bf16 v[106:109], v[50:53], v[166:169], v[106:109]
	s_waitcnt lgkmcnt(3)
	v_mfma_f32_16x16x32_bf16 v[90:93], v[54:57], v[138:141], v[90:93]
	v_mfma_f32_16x16x32_bf16 v[94:97], v[54:57], v[158:161], v[94:97]
	v_mfma_f32_16x16x32_bf16 v[82:85], v[54:57], v[162:165], v[82:85]
	v_mfma_f32_16x16x32_bf16 v[86:89], v[54:57], v[166:169], v[86:89]
	s_waitcnt lgkmcnt(1)
	v_mfma_f32_16x16x32_bf16 v[70:73], v[58:61], v[138:141], v[70:73]
	v_mfma_f32_16x16x32_bf16 v[74:77], v[58:61], v[158:161], v[74:77]
	v_mfma_f32_16x16x32_bf16 v[62:65], v[58:61], v[162:165], v[62:65]
	v_mfma_f32_16x16x32_bf16 v[66:69], v[58:61], v[166:169], v[66:69]
	s_waitcnt lgkmcnt(0)
	s_add_i32 s13, s13, 0x10000
	s_addk_i32 s15, 0x80
	s_barrier
	v_mfma_f32_16x16x32_bf16 v[42:45], v[232:235], v[138:141], v[42:45]
	v_mfma_f32_16x16x32_bf16 v[46:49], v[232:235], v[158:161], v[46:49]
	v_mfma_f32_16x16x32_bf16 v[34:37], v[232:235], v[162:165], v[34:37]
	v_mfma_f32_16x16x32_bf16 v[38:41], v[232:235], v[166:169], v[38:41]
	v_mfma_f32_16x16x32_bf16 v[26:29], v[236:239], v[138:141], v[26:29]
	v_mfma_f32_16x16x32_bf16 v[30:33], v[236:239], v[158:161], v[30:33]
	v_mfma_f32_16x16x32_bf16 v[18:21], v[236:239], v[162:165], v[18:21]
	v_mfma_f32_16x16x32_bf16 v[22:25], v[236:239], v[166:169], v[22:25]
	v_mfma_f32_16x16x32_bf16 v[10:13], v[240:243], v[138:141], v[10:13]
	v_mfma_f32_16x16x32_bf16 v[14:17], v[240:243], v[158:161], v[14:17]
	v_mfma_f32_16x16x32_bf16 v[2:5], v[240:243], v[162:165], v[2:5]
	v_mfma_f32_16x16x32_bf16 v[6:9], v[240:243], v[166:169], v[6:9]
	s_nop 7
	s_nop 7
	s_nop 3
